# GEMM loops (P1 peel + loop, P3, P4): back-edge counter/pointer SALU rotated ahead of the phase-final barrier
# baseline (speedup 1.0000x reference)
; #define PG8_STAGE(bufoff, gbase, voff) do { _Pragma("unroll") for (int _i = 0; _i < 2; ++_i) \
;         __builtin_amdgcn_global_load_lds((const unsigned*)((const char*)(gbase) + (voff)[_i]), (PG8_LAS unsigned*)(lds + (bufoff) + ldsw + _i * 8192), 16, 0, 0); } while (0)
; #define PG8_LDA(dst, b, h) do { _Pragma("unroll") for (int m = 0; m < 4; ++m) _Pragma("unroll") for (int k = 0; k < 2; ++k) dst[m][k] = *(const PG8_LAS bf16x8*)(lds + PG8_SA(b, h) + aoff + m * 2048 + k * 1024); } while (0)
; #define PG8_LDB(dst, b, h) do { _Pragma("unroll") for (int n = 0; n < 2; ++n) _Pragma("unroll") for (int k = 0; k < 2; ++k) dst[n][k] = *(const PG8_LAS bf16x8*)(lds + PG8_SB(b, h) + boff + n * 2048 + k * 1024); } while (0)
; #define PG8_MMA(ai, bj, At, Bt) do { __builtin_amdgcn_s_setprio(1); _Pragma("unroll") for (int m = 0; m < 4; ++m) _Pragma("unroll") for (int n = 0; n < 2; ++n) _Pragma("unroll") for (int k = 0; k < 2; ++k) \
;         acc[ai][bj][m][n] = __builtin_amdgcn_mfma_f32_16x16x32_bf16(Bt[n][k], At[m][k], acc[ai][bj][m][n], 0, 0, 0); __builtin_amdgcn_s_setprio(0); } while (0)
; #define PG8_WAIT_V(n) asm volatile("s_waitcnt vmcnt(" #n ")" ::: "memory")
; #define PG8_BAR __builtin_amdgcn_s_barrier()
; template <class Epi, class Sched, bool ALIGN_EPI>
; __device__ __forceinline__ unsigned long long gemm_phase(PG8_LAS unsigned char* lds, const Gemm g, const Sched& S, const Epi& E, const int probe_id) {
;     ...
;         const char* nA = has_next ? (const char*)g.A + (size_t)nxt.pm * tstepA + (size_t)nxt.kp * K * 2 : cA; const char* nB = has_next ? (const char*)g.Bt + (size_t)nxt.pn * tstepB + (size_t)nxt.kp * K * 2 : cB;
;         for (int t = 0; t < nt; t += 2) {
;             const bool last = (t == nt - 2);
;             const char* a1 = cA + (size_t)(t + 1) * kstep;
;             const char* a2 = last ? nA : cA + (size_t)(t + 2) * kstep; const char* b2 = last ? nB : cB + (size_t)(t + 2) * kstep;
;             const char* a3 = a2 + kstep; const char* b3 = b2 + kstep;
;             PG8_LDB(B0, 0, 0); PG8_LDB(B1, 0, 1); PG8_SCHED; PG8_LDA(At, 0, 0); PG8_STAGE(PG8_SA(1, 1), a1 + hstepA, voffA);
;             PG8_WAIT_V(8); PG8_WAIT_L(0); PG8_BAR; PG8_MMA(0, 0, At, B0); PG8_MMA(0, 1, At, B1); PG8_BAR; PG8_SCHED;
;             PG8_LDA(At, 0, 1); PG8_STAGE(PG8_SB(0, 0), b2, voffB); PG8_STAGE(PG8_SB(0, 1), b2 + hstepB, voffB); PG8_STAGE(PG8_SA(0, 0), a2, voffA);
.LBB0_126:
	s_mov_b32 s68, s29
	s_ashr_i32 s69, s29, 31
	s_lshl_b64 s[10:11], s[68:69], 19
	s_add_u32 s80, s3, s10
	s_addc_u32 s81, s12, s11
	s_mov_b32 s70, s5
	s_and_b64 s[10:11], s[78:79], exec
	s_cselect_b32 s2, s81, s7
	s_cselect_b32 s5, s80, s6
	s_ashr_i32 s71, s70, 31
	s_lshl_b64 s[10:11], s[70:71], 19
	s_add_u32 s82, s13, s10
	s_addc_u32 s83, s14, s11
	s_and_b64 s[10:11], s[78:79], exec
	s_cselect_b32 s29, s83, s9
	s_cselect_b32 s56, s82, s8
	s_add_u32 s6, s6, 0x40080
	s_addc_u32 s7, s7, 0
	s_add_u32 s69, s8, 0x100
	s_addc_u32 s71, s9, 0
	s_mov_b32 s76, -2
	ds_read_b128 v[130:133], v180
	ds_read_b128 v[134:137], v180 offset:1024
	ds_read_b128 v[138:141], v180 offset:2048
	ds_read_b128 v[142:145], v180 offset:3072
	ds_read_b128 v[164:167], v181
	ds_read_b128 v[168:171], v181 offset:1024
	ds_read_b128 v[172:175], v181 offset:2048
	ds_read_b128 v[188:191], v181 offset:3072
	s_add_u32 s8, s6, 0xfffc0080
	s_addc_u32 s9, s7, -1
	s_cmp_eq_u32 s76, 12
	s_cselect_b32 s11, s2, s9
	s_cselect_b32 s10, s5, s8
	s_cselect_b32 s9, s29, s71
	s_cselect_b32 s8, s56, s69
	v_lshl_add_u64 v[176:177], s[6:7], 0, v[158:159]
	s_add_i32 m0, s34, 0xc000
	ds_read_b128 v[192:195], v182
	ds_read_b128 v[196:199], v182 offset:1024
	ds_read_b128 v[200:203], v182 offset:2048
	ds_read_b128 v[204:207], v182 offset:3072
	ds_read_b128 v[208:211], v182 offset:4096
	ds_read_b128 v[212:215], v182 offset:5120
	ds_read_b128 v[216:219], v182 offset:6144
	ds_read_b128 v[220:223], v182 offset:7168
	global_load_lds_dwordx4 v[176:177], off
	v_lshl_add_u64 v[176:177], s[6:7], 0, v[160:161]
	s_add_i32 m0, s34, 0xe000
	s_nop 0
	global_load_lds_dwordx4 v[176:177], off
	s_waitcnt vmcnt(8)
	s_waitcnt lgkmcnt(0)
	s_barrier
	s_setprio 1
	s_waitcnt lgkmcnt(0)
	v_mfma_f32_16x16x32_bf16 v[126:129], v[130:133], v[192:195], 0
	v_mfma_f32_16x16x32_bf16 v[122:125], v[138:141], v[192:195], 0
	v_mfma_f32_16x16x32_bf16 v[110:113], v[130:133], v[200:203], 0
	v_mfma_f32_16x16x32_bf16 v[106:109], v[138:141], v[200:203], 0
	v_mfma_f32_16x16x32_bf16 v[94:97], v[130:133], v[208:211], 0
	v_mfma_f32_16x16x32_bf16 v[90:93], v[138:141], v[208:211], 0
	v_mfma_f32_16x16x32_bf16 v[78:81], v[130:133], v[216:219], 0
	v_mfma_f32_16x16x32_bf16 v[74:77], v[138:141], v[216:219], 0
	v_mfma_f32_16x16x32_bf16 v[126:129], v[134:137], v[196:199], v[126:129]
	v_mfma_f32_16x16x32_bf16 v[122:125], v[142:145], v[196:199], v[122:125]
	v_mfma_f32_16x16x32_bf16 v[110:113], v[134:137], v[204:207], v[110:113]
	v_mfma_f32_16x16x32_bf16 v[106:109], v[142:145], v[204:207], v[106:109]
	v_mfma_f32_16x16x32_bf16 v[94:97], v[134:137], v[212:215], v[94:97]
	v_mfma_f32_16x16x32_bf16 v[90:93], v[142:145], v[212:215], v[90:93]
	v_mfma_f32_16x16x32_bf16 v[78:81], v[134:137], v[220:223], v[78:81]
	v_mfma_f32_16x16x32_bf16 v[74:77], v[142:145], v[220:223], v[74:77]
	s_setprio 0
	s_setprio 1
	v_mfma_f32_16x16x32_bf16 v[118:121], v[164:167], v[192:195], 0
	v_mfma_f32_16x16x32_bf16 v[114:117], v[172:175], v[192:195], 0
	v_mfma_f32_16x16x32_bf16 v[102:105], v[164:167], v[200:203], 0
	v_mfma_f32_16x16x32_bf16 v[98:101], v[172:175], v[200:203], 0
	v_mfma_f32_16x16x32_bf16 v[86:89], v[164:167], v[208:211], 0
	v_mfma_f32_16x16x32_bf16 v[82:85], v[172:175], v[208:211], 0
	v_mfma_f32_16x16x32_bf16 v[70:73], v[164:167], v[216:219], 0
	v_mfma_f32_16x16x32_bf16 v[66:69], v[172:175], v[216:219], 0
	v_mfma_f32_16x16x32_bf16 v[118:121], v[168:171], v[196:199], v[118:121]
	v_mfma_f32_16x16x32_bf16 v[114:117], v[188:191], v[196:199], v[114:117]
	v_mfma_f32_16x16x32_bf16 v[102:105], v[168:171], v[204:207], v[102:105]
	v_mfma_f32_16x16x32_bf16 v[98:101], v[188:191], v[204:207], v[98:101]
	v_mfma_f32_16x16x32_bf16 v[86:89], v[168:171], v[212:215], v[86:89]
	v_mfma_f32_16x16x32_bf16 v[82:85], v[188:191], v[212:215], v[82:85]
	v_mfma_f32_16x16x32_bf16 v[70:73], v[168:171], v[220:223], v[70:73]
	v_mfma_f32_16x16x32_bf16 v[66:69], v[188:191], v[220:223], v[66:69]
	s_setprio 0
	s_barrier
	s_add_i32 s86, s57, s15
	v_lshl_add_u64 v[176:177], s[8:9], 0, v[150:151]
	s_mov_b32 m0, s86
	ds_read_b128 v[192:195], v182 offset:16384
	ds_read_b128 v[196:199], v182 offset:17408
	ds_read_b128 v[200:203], v182 offset:18432
	ds_read_b128 v[204:207], v182 offset:19456
	ds_read_b128 v[208:211], v182 offset:20480
	ds_read_b128 v[212:215], v182 offset:21504
	ds_read_b128 v[216:219], v182 offset:22528
	ds_read_b128 v[220:223], v182 offset:23552
	global_load_lds_dwordx4 v[176:177], off
	s_add_i32 m0, s86, 0x2000
	s_add_u32 s86, s8, 0x40000
	v_lshl_add_u64 v[224:225], s[8:9], 0, v[154:155]
	s_addc_u32 s87, s9, 0
	s_add_i32 s88, s60, s15
	global_load_lds_dwordx4 v[224:225], off
	v_lshl_add_u64 v[226:227], s[86:87], 0, v[150:151]
	s_mov_b32 m0, s88
	v_lshl_add_u64 v[228:229], s[10:11], 0, v[152:153]
	global_load_lds_dwordx4 v[226:227], off
	v_lshl_add_u64 v[226:227], s[86:87], 0, v[154:155]
	s_add_i32 m0, s88, 0x2000
	s_nop 0
	global_load_lds_dwordx4 v[226:227], off
	v_lshl_add_u64 v[226:227], s[10:11], 0, v[148:149]
	s_mov_b32 m0, s34
	s_nop 0
	global_load_lds_dwordx4 v[226:227], off
	s_mov_b32 m0, s35
	s_nop 0
	global_load_lds_dwordx4 v[228:229], off
	s_waitcnt vmcnt(8)
	s_waitcnt lgkmcnt(0)
	s_barrier
; #define PG8_STAGE(bufoff, gbase, voff) do { _Pragma("unroll") for (int _i = 0; _i < 2; ++_i) \
;         __builtin_amdgcn_global_load_lds((const unsigned*)((const char*)(gbase) + (voff)[_i]), (PG8_LAS unsigned*)(lds + (bufoff) + ldsw + _i * 8192), 16, 0, 0); } while (0)
; #define PG8_LDA(dst, b, h) do { _Pragma("unroll") for (int m = 0; m < 4; ++m) _Pragma("unroll") for (int k = 0; k < 2; ++k) dst[m][k] = *(const PG8_LAS bf16x8*)(lds + PG8_SA(b, h) + aoff + m * 2048 + k * 1024); } while (0)
; #define PG8_LDB(dst, b, h) do { _Pragma("unroll") for (int n = 0; n < 2; ++n) _Pragma("unroll") for (int k = 0; k < 2; ++k) dst[n][k] = *(const PG8_LAS bf16x8*)(lds + PG8_SB(b, h) + boff + n * 2048 + k * 1024); } while (0)
; #define PG8_MMA(ai, bj, At, Bt) do { __builtin_amdgcn_s_setprio(1); _Pragma("unroll") for (int m = 0; m < 4; ++m) _Pragma("unroll") for (int n = 0; n < 2; ++n) _Pragma("unroll") for (int k = 0; k < 2; ++k) \
;         acc[ai][bj][m][n] = __builtin_amdgcn_mfma_f32_16x16x32_bf16(Bt[n][k], At[m][k], acc[ai][bj][m][n], 0, 0, 0); __builtin_amdgcn_s_setprio(0); } while (0)
; #define PG8_WAIT_V(n) asm volatile("s_waitcnt vmcnt(" #n ")" ::: "memory")
; #define PG8_WAIT_L(n) asm volatile("s_waitcnt lgkmcnt(" #n ")" ::: "memory")
; #define PG8_BAR __builtin_amdgcn_s_barrier()
; #define PG8_SCHED __builtin_amdgcn_sched_barrier(0)
; template <class Epi, class Sched, bool ALIGN_EPI>
; __device__ __forceinline__ unsigned long long gemm_phase(PG8_LAS unsigned char* lds, const Gemm g, const Sched& S, const Epi& E, const int probe_id) {
;     ...
;             PG8_WAIT_V(8); PG8_WAIT_L(0); PG8_BAR; PG8_MMA(1, 0, At, B0); PG8_MMA(1, 1, At, B1); PG8_BAR; PG8_SCHED;
;             PG8_LDB(B0, 1, 0); PG8_LDB(B1, 1, 1); PG8_SCHED; PG8_LDA(At, 1, 0); PG8_STAGE(PG8_SA(0, 1), a2 + hstepA, voffA);
;             PG8_WAIT_V(8); PG8_WAIT_L(0); PG8_BAR; PG8_MMA(0, 0, At, B0); PG8_MMA(0, 1, At, B1); PG8_BAR; PG8_SCHED;
	s_setprio 1
	s_waitcnt lgkmcnt(0)
	v_mfma_f32_16x16x32_bf16 v[62:65], v[130:133], v[192:195], 0
	v_mfma_f32_16x16x32_bf16 v[58:61], v[138:141], v[192:195], 0
	v_mfma_f32_16x16x32_bf16 v[46:49], v[130:133], v[200:203], 0
	v_mfma_f32_16x16x32_bf16 v[42:45], v[138:141], v[200:203], 0
	v_mfma_f32_16x16x32_bf16 v[30:33], v[130:133], v[208:211], 0
	v_mfma_f32_16x16x32_bf16 v[26:29], v[138:141], v[208:211], 0
	v_mfma_f32_16x16x32_bf16 v[14:17], v[130:133], v[216:219], 0
	v_mfma_f32_16x16x32_bf16 v[10:13], v[138:141], v[216:219], 0
	v_mfma_f32_16x16x32_bf16 v[62:65], v[134:137], v[196:199], v[62:65]
	v_mfma_f32_16x16x32_bf16 v[58:61], v[142:145], v[196:199], v[58:61]
	v_mfma_f32_16x16x32_bf16 v[46:49], v[134:137], v[204:207], v[46:49]
	v_mfma_f32_16x16x32_bf16 v[42:45], v[142:145], v[204:207], v[42:45]
	v_mfma_f32_16x16x32_bf16 v[30:33], v[134:137], v[212:215], v[30:33]
	v_mfma_f32_16x16x32_bf16 v[26:29], v[142:145], v[212:215], v[26:29]
	v_mfma_f32_16x16x32_bf16 v[14:17], v[134:137], v[220:223], v[14:17]
	v_mfma_f32_16x16x32_bf16 v[10:13], v[142:145], v[220:223], v[10:13]
	s_setprio 0
	s_setprio 1
	v_mfma_f32_16x16x32_bf16 v[54:57], v[164:167], v[192:195], 0
	v_mfma_f32_16x16x32_bf16 v[50:53], v[172:175], v[192:195], 0
	v_mfma_f32_16x16x32_bf16 v[38:41], v[164:167], v[200:203], 0
	v_mfma_f32_16x16x32_bf16 v[34:37], v[172:175], v[200:203], 0
	v_mfma_f32_16x16x32_bf16 v[22:25], v[164:167], v[208:211], 0
	v_mfma_f32_16x16x32_bf16 v[18:21], v[172:175], v[208:211], 0
	v_mfma_f32_16x16x32_bf16 v[6:9], v[164:167], v[216:219], 0
	v_mfma_f32_16x16x32_bf16 v[2:5], v[172:175], v[216:219], 0
	v_mfma_f32_16x16x32_bf16 v[54:57], v[168:171], v[196:199], v[54:57]
	v_mfma_f32_16x16x32_bf16 v[50:53], v[188:191], v[196:199], v[50:53]
	v_mfma_f32_16x16x32_bf16 v[38:41], v[168:171], v[204:207], v[38:41]
	v_mfma_f32_16x16x32_bf16 v[34:37], v[188:191], v[204:207], v[34:37]
	v_mfma_f32_16x16x32_bf16 v[22:25], v[168:171], v[212:215], v[22:25]
	v_mfma_f32_16x16x32_bf16 v[18:21], v[188:191], v[212:215], v[18:21]
	v_mfma_f32_16x16x32_bf16 v[6:9], v[168:171], v[220:223], v[6:9]
	v_mfma_f32_16x16x32_bf16 v[2:5], v[188:191], v[220:223], v[2:5]
	s_setprio 0
	s_barrier
	s_add_i32 s86, 0, 0x18000
	s_add_i32 s87, 0, 0x1c000
	v_add_u32_e32 v142, s86, v147
	v_add_u32_e32 v156, s87, v147
	ds_read_b128 v[130:133], v142
	ds_read_b128 v[134:137], v142 offset:1024
	ds_read_b128 v[138:141], v142 offset:2048
	ds_read_b128 v[142:145], v142 offset:3072
	ds_read_b128 v[164:167], v156
	ds_read_b128 v[168:171], v156 offset:1024
	ds_read_b128 v[172:175], v156 offset:2048
	ds_read_b128 v[188:191], v156 offset:3072
	s_add_u32 s10, s10, 0x40000
	s_addc_u32 s11, s11, 0
	s_mov_b32 m0, s77
	v_lshl_add_u64 v[230:231], s[10:11], 0, v[148:149]
	ds_read_b128 v[192:195], v182 offset:32768
	ds_read_b128 v[196:199], v182 offset:33792
	ds_read_b128 v[200:203], v182 offset:34816
	ds_read_b128 v[204:207], v182 offset:35840
	ds_read_b128 v[208:211], v182 offset:36864
	ds_read_b128 v[212:215], v182 offset:37888
	ds_read_b128 v[216:219], v182 offset:38912
	ds_read_b128 v[220:223], v182 offset:39936
	global_load_lds_dwordx4 v[230:231], off
	v_lshl_add_u64 v[230:231], s[10:11], 0, v[152:153]
	s_mov_b32 m0, s85
	s_nop 0
	global_load_lds_dwordx4 v[230:231], off
	s_waitcnt vmcnt(8)
	s_waitcnt lgkmcnt(0)
	s_barrier
	s_setprio 1
	s_waitcnt lgkmcnt(0)
	v_mfma_f32_16x16x32_bf16 v[126:129], v[130:133], v[192:195], v[126:129]
	v_mfma_f32_16x16x32_bf16 v[122:125], v[138:141], v[192:195], v[122:125]
	v_mfma_f32_16x16x32_bf16 v[110:113], v[130:133], v[200:203], v[110:113]
	v_mfma_f32_16x16x32_bf16 v[106:109], v[138:141], v[200:203], v[106:109]
	v_mfma_f32_16x16x32_bf16 v[94:97], v[130:133], v[208:211], v[94:97]
	v_mfma_f32_16x16x32_bf16 v[90:93], v[138:141], v[208:211], v[90:93]
	v_mfma_f32_16x16x32_bf16 v[78:81], v[130:133], v[216:219], v[78:81]
	v_mfma_f32_16x16x32_bf16 v[74:77], v[138:141], v[216:219], v[74:77]
	v_mfma_f32_16x16x32_bf16 v[126:129], v[134:137], v[196:199], v[126:129]
	v_mfma_f32_16x16x32_bf16 v[122:125], v[142:145], v[196:199], v[122:125]
	v_mfma_f32_16x16x32_bf16 v[110:113], v[134:137], v[204:207], v[110:113]
	v_mfma_f32_16x16x32_bf16 v[106:109], v[142:145], v[204:207], v[106:109]
	v_mfma_f32_16x16x32_bf16 v[94:97], v[134:137], v[212:215], v[94:97]
	v_mfma_f32_16x16x32_bf16 v[90:93], v[142:145], v[212:215], v[90:93]
	v_mfma_f32_16x16x32_bf16 v[78:81], v[134:137], v[220:223], v[78:81]
	v_mfma_f32_16x16x32_bf16 v[74:77], v[142:145], v[220:223], v[74:77]
	s_setprio 0
	s_setprio 1
	v_mfma_f32_16x16x32_bf16 v[118:121], v[164:167], v[192:195], v[118:121]
	v_mfma_f32_16x16x32_bf16 v[114:117], v[172:175], v[192:195], v[114:117]
	v_mfma_f32_16x16x32_bf16 v[102:105], v[164:167], v[200:203], v[102:105]
	v_mfma_f32_16x16x32_bf16 v[98:101], v[172:175], v[200:203], v[98:101]
	v_mfma_f32_16x16x32_bf16 v[86:89], v[164:167], v[208:211], v[86:89]
	v_mfma_f32_16x16x32_bf16 v[82:85], v[172:175], v[208:211], v[82:85]
	v_mfma_f32_16x16x32_bf16 v[70:73], v[164:167], v[216:219], v[70:73]
	v_mfma_f32_16x16x32_bf16 v[66:69], v[172:175], v[216:219], v[66:69]
	v_mfma_f32_16x16x32_bf16 v[118:121], v[168:171], v[196:199], v[118:121]
	v_mfma_f32_16x16x32_bf16 v[114:117], v[188:191], v[196:199], v[114:117]
	v_mfma_f32_16x16x32_bf16 v[102:105], v[168:171], v[204:207], v[102:105]
	v_mfma_f32_16x16x32_bf16 v[98:101], v[188:191], v[204:207], v[98:101]
	v_mfma_f32_16x16x32_bf16 v[86:89], v[168:171], v[212:215], v[86:89]
	v_mfma_f32_16x16x32_bf16 v[82:85], v[188:191], v[212:215], v[82:85]
	v_mfma_f32_16x16x32_bf16 v[70:73], v[168:171], v[220:223], v[70:73]
	v_mfma_f32_16x16x32_bf16 v[66:69], v[188:191], v[220:223], v[66:69]
	s_setprio 0
	s_barrier
; #define PG8_STAGE(bufoff, gbase, voff) do { _Pragma("unroll") for (int _i = 0; _i < 2; ++_i) \
;         __builtin_amdgcn_global_load_lds((const unsigned*)((const char*)(gbase) + (voff)[_i]), (PG8_LAS unsigned*)(lds + (bufoff) + ldsw + _i * 8192), 16, 0, 0); } while (0)
; #define PG8_LDA(dst, b, h) do { _Pragma("unroll") for (int m = 0; m < 4; ++m) _Pragma("unroll") for (int k = 0; k < 2; ++k) dst[m][k] = *(const PG8_LAS bf16x8*)(lds + PG8_SA(b, h) + aoff + m * 2048 + k * 1024); } while (0)
; #define PG8_LDB(dst, b, h) do { _Pragma("unroll") for (int n = 0; n < 2; ++n) _Pragma("unroll") for (int k = 0; k < 2; ++k) dst[n][k] = *(const PG8_LAS bf16x8*)(lds + PG8_SB(b, h) + boff + n * 2048 + k * 1024); } while (0)
; #define PG8_WAIT_V(n) asm volatile("s_waitcnt vmcnt(" #n ")" ::: "memory")
; template <class Epi, class Sched, bool ALIGN_EPI>
; __device__ __forceinline__ unsigned long long gemm_phase(PG8_LAS unsigned char* lds, const Gemm g, const Sched& S, const Epi& E, const int probe_id) {
;     ...
;         for (int t = 0; t < nt; t += 2) {
;             const bool last = (t == nt - 2);
;             const char* a1 = cA + (size_t)(t + 1) * kstep;
;             const char* a2 = last ? nA : cA + (size_t)(t + 2) * kstep; const char* b2 = last ? nB : cB + (size_t)(t + 2) * kstep;
;             const char* a3 = a2 + kstep; const char* b3 = b2 + kstep;
;             PG8_LDB(B0, 0, 0); PG8_LDB(B1, 0, 1); PG8_SCHED; PG8_LDA(At, 0, 0); PG8_STAGE(PG8_SA(1, 1), a1 + hstepA, voffA);
;             PG8_WAIT_V(8); PG8_WAIT_L(0); PG8_BAR; PG8_MMA(0, 0, At, B0); PG8_MMA(0, 1, At, B1); PG8_BAR; PG8_SCHED;
;             PG8_LDA(At, 0, 1); PG8_STAGE(PG8_SB(0, 0), b2, voffB); PG8_STAGE(PG8_SB(0, 1), b2 + hstepB, voffB); PG8_STAGE(PG8_SA(0, 0), a2, voffA);
;             PG8_WAIT_V(8); PG8_WAIT_L(0); PG8_BAR; PG8_MMA(1, 0, At, B0); PG8_MMA(1, 1, At, B1); PG8_BAR; PG8_SCHED;
;             PG8_LDB(B0, 1, 0); PG8_LDB(B1, 1, 1); PG8_SCHED; PG8_LDA(At, 1, 0); PG8_STAGE(PG8_SA(0, 1), a2 + hstepA, voffA);
;             PG8_WAIT_V(8); PG8_WAIT_L(0); PG8_BAR; PG8_MMA(0, 0, At, B0); PG8_MMA(0, 1, At, B1); PG8_BAR; PG8_SCHED;
;             PG8_LDA(At, 1, 1); PG8_STAGE(PG8_SB(1, 0), b3, voffB); PG8_STAGE(PG8_SB(1, 1), b3 + hstepB, voffB); PG8_STAGE(PG8_SA(1, 0), a3, voffA);
;             PG8_WAIT_V(8); PG8_WAIT_L(0); PG8_BAR; PG8_MMA(1, 0, At, B0); PG8_MMA(1, 1, At, B1); PG8_BAR; PG8_SCHED;
	s_add_i32 s10, s86, s15
	v_lshl_add_u64 v[176:177], v[176:177], 0, s[30:31]
	s_mov_b32 m0, s10
	ds_read_b128 v[192:195], v182 offset:49152
	ds_read_b128 v[196:199], v182 offset:50176
	ds_read_b128 v[200:203], v182 offset:51200
	ds_read_b128 v[204:207], v182 offset:52224
	ds_read_b128 v[208:211], v182 offset:53248
	ds_read_b128 v[212:215], v182 offset:54272
	ds_read_b128 v[216:219], v182 offset:55296
	ds_read_b128 v[220:223], v182 offset:56320
	global_load_lds_dwordx4 v[176:177], off
	s_add_i32 m0, s10, 0x2000
	s_add_u32 s8, s8, 0x40080
	v_lshl_add_u64 v[176:177], v[224:225], 0, s[30:31]
	s_addc_u32 s9, s9, 0
	s_add_i32 s10, s87, s15
	global_load_lds_dwordx4 v[176:177], off
	v_lshl_add_u64 v[176:177], s[8:9], 0, v[150:151]
	s_mov_b32 m0, s10
	s_nop 0
	global_load_lds_dwordx4 v[176:177], off
	v_lshl_add_u64 v[176:177], s[8:9], 0, v[154:155]
	s_add_i32 m0, s10, 0x2000
	s_nop 0
	global_load_lds_dwordx4 v[176:177], off
	v_lshl_add_u64 v[176:177], v[226:227], 0, s[30:31]
	s_mov_b32 m0, s95
	s_nop 0
	global_load_lds_dwordx4 v[176:177], off
	v_lshl_add_u64 v[176:177], v[228:229], 0, s[30:31]
	s_mov_b32 m0, s97
	s_nop 0
	global_load_lds_dwordx4 v[176:177], off
	s_waitcnt vmcnt(8)
	s_waitcnt lgkmcnt(0)
	s_barrier
	s_setprio 1
	s_waitcnt lgkmcnt(0)
	v_mfma_f32_16x16x32_bf16 v[62:65], v[130:133], v[192:195], v[62:65]
	v_mfma_f32_16x16x32_bf16 v[58:61], v[138:141], v[192:195], v[58:61]
	v_mfma_f32_16x16x32_bf16 v[46:49], v[130:133], v[200:203], v[46:49]
	v_mfma_f32_16x16x32_bf16 v[42:45], v[138:141], v[200:203], v[42:45]
	v_mfma_f32_16x16x32_bf16 v[30:33], v[130:133], v[208:211], v[30:33]
	v_mfma_f32_16x16x32_bf16 v[26:29], v[138:141], v[208:211], v[26:29]
	v_mfma_f32_16x16x32_bf16 v[14:17], v[130:133], v[216:219], v[14:17]
	v_mfma_f32_16x16x32_bf16 v[10:13], v[138:141], v[216:219], v[10:13]
	v_mfma_f32_16x16x32_bf16 v[62:65], v[134:137], v[196:199], v[62:65]
	v_mfma_f32_16x16x32_bf16 v[58:61], v[142:145], v[196:199], v[58:61]
	v_mfma_f32_16x16x32_bf16 v[46:49], v[134:137], v[204:207], v[46:49]
	v_mfma_f32_16x16x32_bf16 v[42:45], v[142:145], v[204:207], v[42:45]
	v_mfma_f32_16x16x32_bf16 v[30:33], v[134:137], v[212:215], v[30:33]
	v_mfma_f32_16x16x32_bf16 v[26:29], v[142:145], v[212:215], v[26:29]
	v_mfma_f32_16x16x32_bf16 v[14:17], v[134:137], v[220:223], v[14:17]
	v_mfma_f32_16x16x32_bf16 v[10:13], v[142:145], v[220:223], v[10:13]
	s_setprio 0
	s_setprio 1
	v_mfma_f32_16x16x32_bf16 v[54:57], v[164:167], v[192:195], v[54:57]
	v_mfma_f32_16x16x32_bf16 v[50:53], v[172:175], v[192:195], v[50:53]
	v_mfma_f32_16x16x32_bf16 v[38:41], v[164:167], v[200:203], v[38:41]
	v_mfma_f32_16x16x32_bf16 v[34:37], v[172:175], v[200:203], v[34:37]
	v_mfma_f32_16x16x32_bf16 v[22:25], v[164:167], v[208:211], v[22:25]
	v_mfma_f32_16x16x32_bf16 v[18:21], v[172:175], v[208:211], v[18:21]
	v_mfma_f32_16x16x32_bf16 v[6:9], v[164:167], v[216:219], v[6:9]
	v_mfma_f32_16x16x32_bf16 v[2:5], v[172:175], v[216:219], v[2:5]
	v_mfma_f32_16x16x32_bf16 v[54:57], v[168:171], v[196:199], v[54:57]
	v_mfma_f32_16x16x32_bf16 v[50:53], v[188:191], v[196:199], v[50:53]
	v_mfma_f32_16x16x32_bf16 v[38:41], v[168:171], v[204:207], v[38:41]
	v_mfma_f32_16x16x32_bf16 v[34:37], v[188:191], v[204:207], v[34:37]
	v_mfma_f32_16x16x32_bf16 v[22:25], v[168:171], v[212:215], v[22:25]
	v_mfma_f32_16x16x32_bf16 v[18:21], v[188:191], v[212:215], v[18:21]
	v_mfma_f32_16x16x32_bf16 v[6:9], v[168:171], v[220:223], v[6:9]
	v_mfma_f32_16x16x32_bf16 v[2:5], v[188:191], v[220:223], v[2:5]
	s_add_i32 s76, s76, 2
	s_add_u32 s6, s6, 0x100
	s_addc_u32 s7, s7, 0
	s_add_u32 s69, s69, 0x100
	s_addc_u32 s71, s71, 0
	s_setprio 0
	s_barrier
.LBB0_127:
	ds_read_b128 v[130:133], v180
	ds_read_b128 v[134:137], v180 offset:1024
	ds_read_b128 v[138:141], v180 offset:2048
	ds_read_b128 v[142:145], v180 offset:3072
	ds_read_b128 v[164:167], v181
	ds_read_b128 v[168:171], v181 offset:1024
	ds_read_b128 v[172:175], v181 offset:2048
	ds_read_b128 v[188:191], v181 offset:3072
	s_add_u32 s8, s6, 0xfffc0080
	s_addc_u32 s9, s7, -1
	s_cmp_eq_u32 s76, 12
	s_cselect_b32 s11, s2, s9
	s_cselect_b32 s10, s5, s8
	s_cselect_b32 s9, s29, s71
	s_cselect_b32 s8, s56, s69
	v_lshl_add_u64 v[176:177], s[6:7], 0, v[158:159]
	s_add_i32 m0, s34, 0xc000
	ds_read_b128 v[192:195], v182
	ds_read_b128 v[196:199], v182 offset:1024
	ds_read_b128 v[200:203], v182 offset:2048
	ds_read_b128 v[204:207], v182 offset:3072
	ds_read_b128 v[208:211], v182 offset:4096
	ds_read_b128 v[212:215], v182 offset:5120
	ds_read_b128 v[216:219], v182 offset:6144
	ds_read_b128 v[220:223], v182 offset:7168
	global_load_lds_dwordx4 v[176:177], off
	v_lshl_add_u64 v[176:177], s[6:7], 0, v[160:161]
	s_add_i32 m0, s34, 0xe000
	s_nop 0
	global_load_lds_dwordx4 v[176:177], off
	s_waitcnt vmcnt(8)
	s_waitcnt lgkmcnt(0)
	s_barrier
; #define PG8_STAGE(bufoff, gbase, voff) do { _Pragma("unroll") for (int _i = 0; _i < 2; ++_i) \
;         __builtin_amdgcn_global_load_lds((const unsigned*)((const char*)(gbase) + (voff)[_i]), (PG8_LAS unsigned*)(lds + (bufoff) + ldsw + _i * 8192), 16, 0, 0); } while (0)
; #define PG8_LDA(dst, b, h) do { _Pragma("unroll") for (int m = 0; m < 4; ++m) _Pragma("unroll") for (int k = 0; k < 2; ++k) dst[m][k] = *(const PG8_LAS bf16x8*)(lds + PG8_SA(b, h) + aoff + m * 2048 + k * 1024); } while (0)
; #define PG8_MMA(ai, bj, At, Bt) do { __builtin_amdgcn_s_setprio(1); _Pragma("unroll") for (int m = 0; m < 4; ++m) _Pragma("unroll") for (int n = 0; n < 2; ++n) _Pragma("unroll") for (int k = 0; k < 2; ++k) \
;         acc[ai][bj][m][n] = __builtin_amdgcn_mfma_f32_16x16x32_bf16(Bt[n][k], At[m][k], acc[ai][bj][m][n], 0, 0, 0); __builtin_amdgcn_s_setprio(0); } while (0)
; #define PG8_WAIT_V(n) asm volatile("s_waitcnt vmcnt(" #n ")" ::: "memory")
; #define PG8_WAIT_L(n) asm volatile("s_waitcnt lgkmcnt(" #n ")" ::: "memory")
; #define PG8_BAR __builtin_amdgcn_s_barrier()
; #define PG8_SCHED __builtin_amdgcn_sched_barrier(0)
; template <class Epi, class Sched, bool ALIGN_EPI>
; __device__ __forceinline__ unsigned long long gemm_phase(PG8_LAS unsigned char* lds, const Gemm g, const Sched& S, const Epi& E, const int probe_id) {
;     ...
;             PG8_WAIT_V(8); PG8_WAIT_L(0); PG8_BAR; PG8_MMA(0, 0, At, B0); PG8_MMA(0, 1, At, B1); PG8_BAR; PG8_SCHED;
;             PG8_LDA(At, 0, 1); PG8_STAGE(PG8_SB(0, 0), b2, voffB); PG8_STAGE(PG8_SB(0, 1), b2 + hstepB, voffB); PG8_STAGE(PG8_SA(0, 0), a2, voffA);
;             PG8_WAIT_V(8); PG8_WAIT_L(0); PG8_BAR; PG8_MMA(1, 0, At, B0); PG8_MMA(1, 1, At, B1); PG8_BAR; PG8_SCHED;
	s_setprio 1
	s_waitcnt lgkmcnt(0)
	v_mfma_f32_16x16x32_bf16 v[126:129], v[130:133], v[192:195], v[126:129]
	v_mfma_f32_16x16x32_bf16 v[122:125], v[138:141], v[192:195], v[122:125]
	v_mfma_f32_16x16x32_bf16 v[110:113], v[130:133], v[200:203], v[110:113]
	v_mfma_f32_16x16x32_bf16 v[106:109], v[138:141], v[200:203], v[106:109]
	v_mfma_f32_16x16x32_bf16 v[94:97], v[130:133], v[208:211], v[94:97]
	v_mfma_f32_16x16x32_bf16 v[90:93], v[138:141], v[208:211], v[90:93]
	v_mfma_f32_16x16x32_bf16 v[78:81], v[130:133], v[216:219], v[78:81]
	v_mfma_f32_16x16x32_bf16 v[74:77], v[138:141], v[216:219], v[74:77]
	v_mfma_f32_16x16x32_bf16 v[126:129], v[134:137], v[196:199], v[126:129]
	v_mfma_f32_16x16x32_bf16 v[122:125], v[142:145], v[196:199], v[122:125]
	v_mfma_f32_16x16x32_bf16 v[110:113], v[134:137], v[204:207], v[110:113]
	v_mfma_f32_16x16x32_bf16 v[106:109], v[142:145], v[204:207], v[106:109]
	v_mfma_f32_16x16x32_bf16 v[94:97], v[134:137], v[212:215], v[94:97]
	v_mfma_f32_16x16x32_bf16 v[90:93], v[142:145], v[212:215], v[90:93]
	v_mfma_f32_16x16x32_bf16 v[78:81], v[134:137], v[220:223], v[78:81]
	v_mfma_f32_16x16x32_bf16 v[74:77], v[142:145], v[220:223], v[74:77]
	s_setprio 0
	s_setprio 1
	v_mfma_f32_16x16x32_bf16 v[118:121], v[164:167], v[192:195], v[118:121]
	v_mfma_f32_16x16x32_bf16 v[114:117], v[172:175], v[192:195], v[114:117]
	v_mfma_f32_16x16x32_bf16 v[102:105], v[164:167], v[200:203], v[102:105]
	v_mfma_f32_16x16x32_bf16 v[98:101], v[172:175], v[200:203], v[98:101]
	v_mfma_f32_16x16x32_bf16 v[86:89], v[164:167], v[208:211], v[86:89]
	v_mfma_f32_16x16x32_bf16 v[82:85], v[172:175], v[208:211], v[82:85]
	v_mfma_f32_16x16x32_bf16 v[70:73], v[164:167], v[216:219], v[70:73]
	v_mfma_f32_16x16x32_bf16 v[66:69], v[172:175], v[216:219], v[66:69]
	v_mfma_f32_16x16x32_bf16 v[118:121], v[168:171], v[196:199], v[118:121]
	v_mfma_f32_16x16x32_bf16 v[114:117], v[188:191], v[196:199], v[114:117]
	v_mfma_f32_16x16x32_bf16 v[102:105], v[168:171], v[204:207], v[102:105]
	v_mfma_f32_16x16x32_bf16 v[98:101], v[188:191], v[204:207], v[98:101]
	v_mfma_f32_16x16x32_bf16 v[86:89], v[168:171], v[212:215], v[86:89]
	v_mfma_f32_16x16x32_bf16 v[82:85], v[188:191], v[212:215], v[82:85]
	v_mfma_f32_16x16x32_bf16 v[70:73], v[168:171], v[220:223], v[70:73]
	v_mfma_f32_16x16x32_bf16 v[66:69], v[188:191], v[220:223], v[66:69]
	s_setprio 0
	s_barrier
	s_add_i32 s86, s57, s15
	v_lshl_add_u64 v[176:177], s[8:9], 0, v[150:151]
	s_mov_b32 m0, s86
	ds_read_b128 v[192:195], v182 offset:16384
	ds_read_b128 v[196:199], v182 offset:17408
	ds_read_b128 v[200:203], v182 offset:18432
	ds_read_b128 v[204:207], v182 offset:19456
	ds_read_b128 v[208:211], v182 offset:20480
	ds_read_b128 v[212:215], v182 offset:21504
	ds_read_b128 v[216:219], v182 offset:22528
	ds_read_b128 v[220:223], v182 offset:23552
	global_load_lds_dwordx4 v[176:177], off
	s_add_i32 m0, s86, 0x2000
	s_add_u32 s86, s8, 0x40000
	v_lshl_add_u64 v[224:225], s[8:9], 0, v[154:155]
	s_addc_u32 s87, s9, 0
	s_add_i32 s88, s60, s15
	global_load_lds_dwordx4 v[224:225], off
	v_lshl_add_u64 v[226:227], s[86:87], 0, v[150:151]
	s_mov_b32 m0, s88
	v_lshl_add_u64 v[228:229], s[10:11], 0, v[152:153]
	global_load_lds_dwordx4 v[226:227], off
	v_lshl_add_u64 v[226:227], s[86:87], 0, v[154:155]
	s_add_i32 m0, s88, 0x2000
	s_nop 0
	global_load_lds_dwordx4 v[226:227], off
	v_lshl_add_u64 v[226:227], s[10:11], 0, v[148:149]
	s_mov_b32 m0, s34
	s_nop 0
	global_load_lds_dwordx4 v[226:227], off
	s_mov_b32 m0, s35
	s_nop 0
	global_load_lds_dwordx4 v[228:229], off
	s_waitcnt vmcnt(8)
	s_waitcnt lgkmcnt(0)
	s_barrier
	s_setprio 1
	s_waitcnt lgkmcnt(0)
	v_mfma_f32_16x16x32_bf16 v[62:65], v[130:133], v[192:195], v[62:65]
	v_mfma_f32_16x16x32_bf16 v[58:61], v[138:141], v[192:195], v[58:61]
	v_mfma_f32_16x16x32_bf16 v[46:49], v[130:133], v[200:203], v[46:49]
	v_mfma_f32_16x16x32_bf16 v[42:45], v[138:141], v[200:203], v[42:45]
	v_mfma_f32_16x16x32_bf16 v[30:33], v[130:133], v[208:211], v[30:33]
	v_mfma_f32_16x16x32_bf16 v[26:29], v[138:141], v[208:211], v[26:29]
	v_mfma_f32_16x16x32_bf16 v[14:17], v[130:133], v[216:219], v[14:17]
	v_mfma_f32_16x16x32_bf16 v[10:13], v[138:141], v[216:219], v[10:13]
	v_mfma_f32_16x16x32_bf16 v[62:65], v[134:137], v[196:199], v[62:65]
	v_mfma_f32_16x16x32_bf16 v[58:61], v[142:145], v[196:199], v[58:61]
	v_mfma_f32_16x16x32_bf16 v[46:49], v[134:137], v[204:207], v[46:49]
	v_mfma_f32_16x16x32_bf16 v[42:45], v[142:145], v[204:207], v[42:45]
	v_mfma_f32_16x16x32_bf16 v[30:33], v[134:137], v[212:215], v[30:33]
	v_mfma_f32_16x16x32_bf16 v[26:29], v[142:145], v[212:215], v[26:29]
	v_mfma_f32_16x16x32_bf16 v[14:17], v[134:137], v[220:223], v[14:17]
	v_mfma_f32_16x16x32_bf16 v[10:13], v[142:145], v[220:223], v[10:13]
	s_setprio 0
	s_setprio 1
	v_mfma_f32_16x16x32_bf16 v[54:57], v[164:167], v[192:195], v[54:57]
	v_mfma_f32_16x16x32_bf16 v[50:53], v[172:175], v[192:195], v[50:53]
	v_mfma_f32_16x16x32_bf16 v[38:41], v[164:167], v[200:203], v[38:41]
	v_mfma_f32_16x16x32_bf16 v[34:37], v[172:175], v[200:203], v[34:37]
	v_mfma_f32_16x16x32_bf16 v[22:25], v[164:167], v[208:211], v[22:25]
	v_mfma_f32_16x16x32_bf16 v[18:21], v[172:175], v[208:211], v[18:21]
	v_mfma_f32_16x16x32_bf16 v[6:9], v[164:167], v[216:219], v[6:9]
	v_mfma_f32_16x16x32_bf16 v[2:5], v[172:175], v[216:219], v[2:5]
	v_mfma_f32_16x16x32_bf16 v[54:57], v[168:171], v[196:199], v[54:57]
	v_mfma_f32_16x16x32_bf16 v[50:53], v[188:191], v[196:199], v[50:53]
	v_mfma_f32_16x16x32_bf16 v[38:41], v[168:171], v[204:207], v[38:41]
	v_mfma_f32_16x16x32_bf16 v[34:37], v[188:191], v[204:207], v[34:37]
	v_mfma_f32_16x16x32_bf16 v[22:25], v[168:171], v[212:215], v[22:25]
	v_mfma_f32_16x16x32_bf16 v[18:21], v[188:191], v[212:215], v[18:21]
	v_mfma_f32_16x16x32_bf16 v[6:9], v[168:171], v[220:223], v[6:9]
	v_mfma_f32_16x16x32_bf16 v[2:5], v[188:191], v[220:223], v[2:5]
	s_setprio 0
	s_barrier
; #define PG8_STAGE(bufoff, gbase, voff) do { _Pragma("unroll") for (int _i = 0; _i < 2; ++_i) \
;         __builtin_amdgcn_global_load_lds((const unsigned*)((const char*)(gbase) + (voff)[_i]), (PG8_LAS unsigned*)(lds + (bufoff) + ldsw + _i * 8192), 16, 0, 0); } while (0)
; #define PG8_LDA(dst, b, h) do { _Pragma("unroll") for (int m = 0; m < 4; ++m) _Pragma("unroll") for (int k = 0; k < 2; ++k) dst[m][k] = *(const PG8_LAS bf16x8*)(lds + PG8_SA(b, h) + aoff + m * 2048 + k * 1024); } while (0)
; #define PG8_LDB(dst, b, h) do { _Pragma("unroll") for (int n = 0; n < 2; ++n) _Pragma("unroll") for (int k = 0; k < 2; ++k) dst[n][k] = *(const PG8_LAS bf16x8*)(lds + PG8_SB(b, h) + boff + n * 2048 + k * 1024); } while (0)
; #define PG8_MMA(ai, bj, At, Bt) do { __builtin_amdgcn_s_setprio(1); _Pragma("unroll") for (int m = 0; m < 4; ++m) _Pragma("unroll") for (int n = 0; n < 2; ++n) _Pragma("unroll") for (int k = 0; k < 2; ++k) \
;         acc[ai][bj][m][n] = __builtin_amdgcn_mfma_f32_16x16x32_bf16(Bt[n][k], At[m][k], acc[ai][bj][m][n], 0, 0, 0); __builtin_amdgcn_s_setprio(0); } while (0)
; #define PG8_WAIT_V(n) asm volatile("s_waitcnt vmcnt(" #n ")" ::: "memory")
; #define PG8_WAIT_L(n) asm volatile("s_waitcnt lgkmcnt(" #n ")" ::: "memory")
; #define PG8_BAR __builtin_amdgcn_s_barrier()
; #define PG8_SCHED __builtin_amdgcn_sched_barrier(0)
; template <class Epi, class Sched, bool ALIGN_EPI>
; __device__ __forceinline__ unsigned long long gemm_phase(PG8_LAS unsigned char* lds, const Gemm g, const Sched& S, const Epi& E, const int probe_id) {
;     ...
;             PG8_LDB(B0, 1, 0); PG8_LDB(B1, 1, 1); PG8_SCHED; PG8_LDA(At, 1, 0); PG8_STAGE(PG8_SA(0, 1), a2 + hstepA, voffA);
;             PG8_WAIT_V(8); PG8_WAIT_L(0); PG8_BAR; PG8_MMA(0, 0, At, B0); PG8_MMA(0, 1, At, B1); PG8_BAR; PG8_SCHED;
	s_add_i32 s86, 0, 0x18000
	s_add_i32 s87, 0, 0x1c000
	v_add_u32_e32 v142, s86, v147
	v_add_u32_e32 v156, s87, v147
	ds_read_b128 v[130:133], v142
	ds_read_b128 v[134:137], v142 offset:1024
	ds_read_b128 v[138:141], v142 offset:2048
	ds_read_b128 v[142:145], v142 offset:3072
	ds_read_b128 v[164:167], v156
	ds_read_b128 v[168:171], v156 offset:1024
	ds_read_b128 v[172:175], v156 offset:2048
	ds_read_b128 v[188:191], v156 offset:3072
	s_add_u32 s10, s10, 0x40000
	s_addc_u32 s11, s11, 0
	s_mov_b32 m0, s77
	v_lshl_add_u64 v[230:231], s[10:11], 0, v[148:149]
	ds_read_b128 v[192:195], v182 offset:32768
	ds_read_b128 v[196:199], v182 offset:33792
	ds_read_b128 v[200:203], v182 offset:34816
	ds_read_b128 v[204:207], v182 offset:35840
	ds_read_b128 v[208:211], v182 offset:36864
	ds_read_b128 v[212:215], v182 offset:37888
	ds_read_b128 v[216:219], v182 offset:38912
	ds_read_b128 v[220:223], v182 offset:39936
	global_load_lds_dwordx4 v[230:231], off
	v_lshl_add_u64 v[230:231], s[10:11], 0, v[152:153]
	s_mov_b32 m0, s85
	s_nop 0
	global_load_lds_dwordx4 v[230:231], off
	s_waitcnt vmcnt(8)
	s_waitcnt lgkmcnt(0)
	s_barrier
	s_setprio 1
	s_waitcnt lgkmcnt(0)
	v_mfma_f32_16x16x32_bf16 v[126:129], v[130:133], v[192:195], v[126:129]
	v_mfma_f32_16x16x32_bf16 v[122:125], v[138:141], v[192:195], v[122:125]
	v_mfma_f32_16x16x32_bf16 v[110:113], v[130:133], v[200:203], v[110:113]
	v_mfma_f32_16x16x32_bf16 v[106:109], v[138:141], v[200:203], v[106:109]
	v_mfma_f32_16x16x32_bf16 v[94:97], v[130:133], v[208:211], v[94:97]
	v_mfma_f32_16x16x32_bf16 v[90:93], v[138:141], v[208:211], v[90:93]
	v_mfma_f32_16x16x32_bf16 v[78:81], v[130:133], v[216:219], v[78:81]
	v_mfma_f32_16x16x32_bf16 v[74:77], v[138:141], v[216:219], v[74:77]
	v_mfma_f32_16x16x32_bf16 v[126:129], v[134:137], v[196:199], v[126:129]
	v_mfma_f32_16x16x32_bf16 v[122:125], v[142:145], v[196:199], v[122:125]
	v_mfma_f32_16x16x32_bf16 v[110:113], v[134:137], v[204:207], v[110:113]
	v_mfma_f32_16x16x32_bf16 v[106:109], v[142:145], v[204:207], v[106:109]
	v_mfma_f32_16x16x32_bf16 v[94:97], v[134:137], v[212:215], v[94:97]
	v_mfma_f32_16x16x32_bf16 v[90:93], v[142:145], v[212:215], v[90:93]
	v_mfma_f32_16x16x32_bf16 v[78:81], v[134:137], v[220:223], v[78:81]
	v_mfma_f32_16x16x32_bf16 v[74:77], v[142:145], v[220:223], v[74:77]
	s_setprio 0
	s_setprio 1
	v_mfma_f32_16x16x32_bf16 v[118:121], v[164:167], v[192:195], v[118:121]
	v_mfma_f32_16x16x32_bf16 v[114:117], v[172:175], v[192:195], v[114:117]
	v_mfma_f32_16x16x32_bf16 v[102:105], v[164:167], v[200:203], v[102:105]
	v_mfma_f32_16x16x32_bf16 v[98:101], v[172:175], v[200:203], v[98:101]
	v_mfma_f32_16x16x32_bf16 v[86:89], v[164:167], v[208:211], v[86:89]
	v_mfma_f32_16x16x32_bf16 v[82:85], v[172:175], v[208:211], v[82:85]
	v_mfma_f32_16x16x32_bf16 v[70:73], v[164:167], v[216:219], v[70:73]
	v_mfma_f32_16x16x32_bf16 v[66:69], v[172:175], v[216:219], v[66:69]
	v_mfma_f32_16x16x32_bf16 v[118:121], v[168:171], v[196:199], v[118:121]
	v_mfma_f32_16x16x32_bf16 v[114:117], v[188:191], v[196:199], v[114:117]
	v_mfma_f32_16x16x32_bf16 v[102:105], v[168:171], v[204:207], v[102:105]
	v_mfma_f32_16x16x32_bf16 v[98:101], v[188:191], v[204:207], v[98:101]
	v_mfma_f32_16x16x32_bf16 v[86:89], v[168:171], v[212:215], v[86:89]
	v_mfma_f32_16x16x32_bf16 v[82:85], v[188:191], v[212:215], v[82:85]
	v_mfma_f32_16x16x32_bf16 v[70:73], v[168:171], v[220:223], v[70:73]
	v_mfma_f32_16x16x32_bf16 v[66:69], v[188:191], v[220:223], v[66:69]
	s_setprio 0
	s_barrier
; #define PG8_STAGE(bufoff, gbase, voff) do { _Pragma("unroll") for (int _i = 0; _i < 2; ++_i) \
;         __builtin_amdgcn_global_load_lds((const unsigned*)((const char*)(gbase) + (voff)[_i]), (PG8_LAS unsigned*)(lds + (bufoff) + ldsw + _i * 8192), 16, 0, 0); } while (0)
; #define PG8_LDA(dst, b, h) do { _Pragma("unroll") for (int m = 0; m < 4; ++m) _Pragma("unroll") for (int k = 0; k < 2; ++k) dst[m][k] = *(const PG8_LAS bf16x8*)(lds + PG8_SA(b, h) + aoff + m * 2048 + k * 1024); } while (0)
; #define PG8_MMA(ai, bj, At, Bt) do { __builtin_amdgcn_s_setprio(1); _Pragma("unroll") for (int m = 0; m < 4; ++m) _Pragma("unroll") for (int n = 0; n < 2; ++n) _Pragma("unroll") for (int k = 0; k < 2; ++k) \
;         acc[ai][bj][m][n] = __builtin_amdgcn_mfma_f32_16x16x32_bf16(Bt[n][k], At[m][k], acc[ai][bj][m][n], 0, 0, 0); __builtin_amdgcn_s_setprio(0); } while (0)
; #define PG8_WAIT_V(n) asm volatile("s_waitcnt vmcnt(" #n ")" ::: "memory")
; #define PG8_WAIT_L(n) asm volatile("s_waitcnt lgkmcnt(" #n ")" ::: "memory")
; #define PG8_BAR __builtin_amdgcn_s_barrier()
; #define PG8_SCHED __builtin_amdgcn_sched_barrier(0)
; template <class Epi, class Sched, bool ALIGN_EPI>
; __device__ __forceinline__ unsigned long long gemm_phase(PG8_LAS unsigned char* lds, const Gemm g, const Sched& S, const Epi& E, const int probe_id) {
;     ...
;             PG8_LDA(At, 1, 1); PG8_STAGE(PG8_SB(1, 0), b3, voffB); PG8_STAGE(PG8_SB(1, 1), b3 + hstepB, voffB); PG8_STAGE(PG8_SA(1, 0), a3, voffA);
;             PG8_WAIT_V(8); PG8_WAIT_L(0); PG8_BAR; PG8_MMA(1, 0, At, B0); PG8_MMA(1, 1, At, B1); PG8_BAR; PG8_SCHED;
;         }
;         if constexpr (ALIGN_EPI) { if (wr == 0) PG8_BAR; }
	s_add_i32 s10, s86, s15
	v_lshl_add_u64 v[176:177], v[176:177], 0, s[30:31]
	s_mov_b32 m0, s10
	ds_read_b128 v[192:195], v182 offset:49152
	ds_read_b128 v[196:199], v182 offset:50176
	ds_read_b128 v[200:203], v182 offset:51200
	ds_read_b128 v[204:207], v182 offset:52224
	ds_read_b128 v[208:211], v182 offset:53248
	ds_read_b128 v[212:215], v182 offset:54272
	ds_read_b128 v[216:219], v182 offset:55296
	ds_read_b128 v[220:223], v182 offset:56320
	global_load_lds_dwordx4 v[176:177], off
	s_add_i32 m0, s10, 0x2000
	s_add_u32 s8, s8, 0x40080
	v_lshl_add_u64 v[176:177], v[224:225], 0, s[30:31]
	s_addc_u32 s9, s9, 0
	s_add_i32 s10, s87, s15
	global_load_lds_dwordx4 v[176:177], off
	v_lshl_add_u64 v[176:177], s[8:9], 0, v[150:151]
	s_mov_b32 m0, s10
	s_nop 0
	global_load_lds_dwordx4 v[176:177], off
	v_lshl_add_u64 v[176:177], s[8:9], 0, v[154:155]
	s_add_i32 m0, s10, 0x2000
	s_nop 0
	global_load_lds_dwordx4 v[176:177], off
	v_lshl_add_u64 v[176:177], v[226:227], 0, s[30:31]
	s_mov_b32 m0, s95
	s_nop 0
	global_load_lds_dwordx4 v[176:177], off
	v_lshl_add_u64 v[176:177], v[228:229], 0, s[30:31]
	s_mov_b32 m0, s97
	s_nop 0
	global_load_lds_dwordx4 v[176:177], off
	s_waitcnt vmcnt(8)
	s_waitcnt lgkmcnt(0)
	s_barrier
	s_setprio 1
	s_waitcnt lgkmcnt(0)
	v_mfma_f32_16x16x32_bf16 v[62:65], v[130:133], v[192:195], v[62:65]
	v_mfma_f32_16x16x32_bf16 v[58:61], v[138:141], v[192:195], v[58:61]
	v_mfma_f32_16x16x32_bf16 v[46:49], v[130:133], v[200:203], v[46:49]
	v_mfma_f32_16x16x32_bf16 v[42:45], v[138:141], v[200:203], v[42:45]
	v_mfma_f32_16x16x32_bf16 v[30:33], v[130:133], v[208:211], v[30:33]
	v_mfma_f32_16x16x32_bf16 v[26:29], v[138:141], v[208:211], v[26:29]
	v_mfma_f32_16x16x32_bf16 v[14:17], v[130:133], v[216:219], v[14:17]
	v_mfma_f32_16x16x32_bf16 v[10:13], v[138:141], v[216:219], v[10:13]
	v_mfma_f32_16x16x32_bf16 v[62:65], v[134:137], v[196:199], v[62:65]
	v_mfma_f32_16x16x32_bf16 v[58:61], v[142:145], v[196:199], v[58:61]
	v_mfma_f32_16x16x32_bf16 v[46:49], v[134:137], v[204:207], v[46:49]
	v_mfma_f32_16x16x32_bf16 v[42:45], v[142:145], v[204:207], v[42:45]
	v_mfma_f32_16x16x32_bf16 v[30:33], v[134:137], v[212:215], v[30:33]
	v_mfma_f32_16x16x32_bf16 v[26:29], v[142:145], v[212:215], v[26:29]
	v_mfma_f32_16x16x32_bf16 v[14:17], v[134:137], v[220:223], v[14:17]
	v_mfma_f32_16x16x32_bf16 v[10:13], v[142:145], v[220:223], v[10:13]
	s_setprio 0
	s_setprio 1
	v_mfma_f32_16x16x32_bf16 v[54:57], v[164:167], v[192:195], v[54:57]
	v_mfma_f32_16x16x32_bf16 v[50:53], v[172:175], v[192:195], v[50:53]
	v_mfma_f32_16x16x32_bf16 v[38:41], v[164:167], v[200:203], v[38:41]
	v_mfma_f32_16x16x32_bf16 v[34:37], v[172:175], v[200:203], v[34:37]
	v_mfma_f32_16x16x32_bf16 v[22:25], v[164:167], v[208:211], v[22:25]
	v_mfma_f32_16x16x32_bf16 v[18:21], v[172:175], v[208:211], v[18:21]
	v_mfma_f32_16x16x32_bf16 v[6:9], v[164:167], v[216:219], v[6:9]
	v_mfma_f32_16x16x32_bf16 v[2:5], v[172:175], v[216:219], v[2:5]
	v_mfma_f32_16x16x32_bf16 v[54:57], v[168:171], v[196:199], v[54:57]
	v_mfma_f32_16x16x32_bf16 v[50:53], v[188:191], v[196:199], v[50:53]
	v_mfma_f32_16x16x32_bf16 v[38:41], v[168:171], v[204:207], v[38:41]
	v_mfma_f32_16x16x32_bf16 v[34:37], v[188:191], v[204:207], v[34:37]
	v_mfma_f32_16x16x32_bf16 v[22:25], v[168:171], v[212:215], v[22:25]
	v_mfma_f32_16x16x32_bf16 v[18:21], v[188:191], v[212:215], v[18:21]
	v_mfma_f32_16x16x32_bf16 v[6:9], v[168:171], v[220:223], v[6:9]
	v_mfma_f32_16x16x32_bf16 v[2:5], v[188:191], v[220:223], v[2:5]
	s_add_i32 s76, s76, 2
	s_add_u32 s6, s6, 0x100
	s_addc_u32 s7, s7, 0
	s_add_u32 s69, s69, 0x100
	s_addc_u32 s71, s71, 0
	s_cmp_gt_u32 s76, 13
	s_setprio 0
	s_barrier
	s_cbranch_scc0 .LBB0_127
	s_and_b64 vcc, exec, s[50:51]
	s_cbranch_vccz .LBB0_130
	s_barrier

; #define PG8_STAGE(bufoff, gbase, voff) do { _Pragma("unroll") for (int _i = 0; _i < 2; ++_i) \
;         __builtin_amdgcn_global_load_lds((const unsigned*)((const char*)(gbase) + (voff)[_i]), (PG8_LAS unsigned*)(lds + (bufoff) + ldsw + _i * 8192), 16, 0, 0); } while (0)
; #define PG8_LDA(dst, b, h) do { _Pragma("unroll") for (int m = 0; m < 4; ++m) _Pragma("unroll") for (int k = 0; k < 2; ++k) dst[m][k] = *(const PG8_LAS bf16x8*)(lds + PG8_SA(b, h) + aoff + m * 2048 + k * 1024); } while (0)
; #define PG8_LDB(dst, b, h) do { _Pragma("unroll") for (int n = 0; n < 2; ++n) _Pragma("unroll") for (int k = 0; k < 2; ++k) dst[n][k] = *(const PG8_LAS bf16x8*)(lds + PG8_SB(b, h) + boff + n * 2048 + k * 1024); } while (0)
; #define PG8_MMA(ai, bj, At, Bt) do { __builtin_amdgcn_s_setprio(1); _Pragma("unroll") for (int m = 0; m < 4; ++m) _Pragma("unroll") for (int n = 0; n < 2; ++n) _Pragma("unroll") for (int k = 0; k < 2; ++k) \
;         acc[ai][bj][m][n] = __builtin_amdgcn_mfma_f32_16x16x32_bf16(Bt[n][k], At[m][k], acc[ai][bj][m][n], 0, 0, 0); __builtin_amdgcn_s_setprio(0); } while (0)
; #define PG8_WAIT_V(n) asm volatile("s_waitcnt vmcnt(" #n ")" ::: "memory")
; #define PG8_WAIT_L(n) asm volatile("s_waitcnt lgkmcnt(" #n ")" ::: "memory")
; #define PG8_BAR __builtin_amdgcn_s_barrier()
; #define PG8_SCHED __builtin_amdgcn_sched_barrier(0)
; template <class Epi, class Sched, bool ALIGN_EPI>
; __device__ __forceinline__ unsigned long long gemm_phase(PG8_LAS unsigned char* lds, const Gemm g, const Sched& S, const Epi& E, const int probe_id) {
;     ...
;         for (int t = 0; t < nt; t += 2) {
;             const bool last = (t == nt - 2);
;             const char* a1 = cA + (size_t)(t + 1) * kstep;
;             const char* a2 = last ? nA : cA + (size_t)(t + 2) * kstep; const char* b2 = last ? nB : cB + (size_t)(t + 2) * kstep;
;             const char* a3 = a2 + kstep; const char* b3 = b2 + kstep;
;             PG8_LDB(B0, 0, 0); PG8_LDB(B1, 0, 1); PG8_SCHED; PG8_LDA(At, 0, 0); PG8_STAGE(PG8_SA(1, 1), a1 + hstepA, voffA);
;             PG8_WAIT_V(8); PG8_WAIT_L(0); PG8_BAR; PG8_MMA(0, 0, At, B0); PG8_MMA(0, 1, At, B1); PG8_BAR; PG8_SCHED;
;             PG8_LDA(At, 0, 1); PG8_STAGE(PG8_SB(0, 0), b2, voffB); PG8_STAGE(PG8_SB(0, 1), b2 + hstepB, voffB); PG8_STAGE(PG8_SA(0, 0), a2, voffA);
.LBB0_621:
	v_add_u32_e32 v158, s56, v160
	ds_read_b128 v[146:149], v158
	ds_read_b128 v[150:153], v158 offset:1024
	ds_read_b128 v[154:157], v158 offset:2048
	ds_read_b128 v[164:167], v158 offset:3072
	v_add_u32_e32 v158, s57, v160
	ds_read_b128 v[168:171], v158
	ds_read_b128 v[172:175], v158 offset:1024
	ds_read_b128 v[176:179], v158 offset:2048
	ds_read_b128 v[180:183], v158 offset:3072
	s_add_u32 s50, s48, 0xfff80080
	s_addc_u32 s51, s49, -1
	s_cmp_eq_u32 s66, 12
	s_cselect_b32 s53, s39, s51
	s_cselect_b32 s52, s41, s50
	s_cselect_b32 s51, s37, s65
	s_cselect_b32 s50, s63, s64
	v_lshl_add_u64 v[158:159], s[48:49], 0, v[138:139]
	s_add_i32 m0, s14, 0xc000
	ds_read_b128 v[184:187], v162
	ds_read_b128 v[188:191], v162 offset:1024
	ds_read_b128 v[192:195], v162 offset:2048
	ds_read_b128 v[196:199], v162 offset:3072
	ds_read_b128 v[200:203], v162 offset:4096
	ds_read_b128 v[204:207], v162 offset:5120
	ds_read_b128 v[208:211], v162 offset:6144
	ds_read_b128 v[212:215], v162 offset:7168
	global_load_lds_dwordx4 v[158:159], off
	v_lshl_add_u64 v[158:159], s[48:49], 0, v[140:141]
	s_add_i32 m0, s14, 0xe000
	s_nop 0
	global_load_lds_dwordx4 v[158:159], off
	s_waitcnt vmcnt(8)
	s_waitcnt lgkmcnt(0)
	s_barrier
	s_setprio 1
	s_waitcnt lgkmcnt(0)
	v_mfma_f32_16x16x32_bf16 v[126:129], v[146:149], v[184:187], v[126:129]
	v_mfma_f32_16x16x32_bf16 v[122:125], v[154:157], v[184:187], v[122:125]
	v_mfma_f32_16x16x32_bf16 v[118:121], v[146:149], v[192:195], v[118:121]
	v_mfma_f32_16x16x32_bf16 v[114:117], v[154:157], v[192:195], v[114:117]
	v_mfma_f32_16x16x32_bf16 v[110:113], v[146:149], v[200:203], v[110:113]
	v_mfma_f32_16x16x32_bf16 v[106:109], v[154:157], v[200:203], v[106:109]
	v_mfma_f32_16x16x32_bf16 v[102:105], v[146:149], v[208:211], v[102:105]
	v_mfma_f32_16x16x32_bf16 v[98:101], v[154:157], v[208:211], v[98:101]
	v_mfma_f32_16x16x32_bf16 v[126:129], v[150:153], v[188:191], v[126:129]
	v_mfma_f32_16x16x32_bf16 v[122:125], v[164:167], v[188:191], v[122:125]
	v_mfma_f32_16x16x32_bf16 v[118:121], v[150:153], v[196:199], v[118:121]
	v_mfma_f32_16x16x32_bf16 v[114:117], v[164:167], v[196:199], v[114:117]
	v_mfma_f32_16x16x32_bf16 v[110:113], v[150:153], v[204:207], v[110:113]
	v_mfma_f32_16x16x32_bf16 v[106:109], v[164:167], v[204:207], v[106:109]
	v_mfma_f32_16x16x32_bf16 v[102:105], v[150:153], v[212:215], v[102:105]
	v_mfma_f32_16x16x32_bf16 v[98:101], v[164:167], v[212:215], v[98:101]
	s_setprio 0
	s_setprio 1
	v_mfma_f32_16x16x32_bf16 v[94:97], v[168:171], v[184:187], v[94:97]
	v_mfma_f32_16x16x32_bf16 v[90:93], v[176:179], v[184:187], v[90:93]
	v_mfma_f32_16x16x32_bf16 v[86:89], v[168:171], v[192:195], v[86:89]
	v_mfma_f32_16x16x32_bf16 v[82:85], v[176:179], v[192:195], v[82:85]
	v_mfma_f32_16x16x32_bf16 v[78:81], v[168:171], v[200:203], v[78:81]
	v_mfma_f32_16x16x32_bf16 v[74:77], v[176:179], v[200:203], v[74:77]
	v_mfma_f32_16x16x32_bf16 v[70:73], v[168:171], v[208:211], v[70:73]
	v_mfma_f32_16x16x32_bf16 v[66:69], v[176:179], v[208:211], v[66:69]
	v_mfma_f32_16x16x32_bf16 v[94:97], v[172:175], v[188:191], v[94:97]
	v_mfma_f32_16x16x32_bf16 v[90:93], v[180:183], v[188:191], v[90:93]
	v_mfma_f32_16x16x32_bf16 v[86:89], v[172:175], v[196:199], v[86:89]
	v_mfma_f32_16x16x32_bf16 v[82:85], v[180:183], v[196:199], v[82:85]
	v_mfma_f32_16x16x32_bf16 v[78:81], v[172:175], v[204:207], v[78:81]
	v_mfma_f32_16x16x32_bf16 v[74:77], v[180:183], v[204:207], v[74:77]
	v_mfma_f32_16x16x32_bf16 v[70:73], v[172:175], v[212:215], v[70:73]
	v_mfma_f32_16x16x32_bf16 v[66:69], v[180:183], v[212:215], v[66:69]
	s_setprio 0
	s_barrier
	s_add_i32 s67, s56, s12
	v_lshl_add_u64 v[158:159], s[50:51], 0, v[132:133]
	s_mov_b32 m0, s67
	ds_read_b128 v[184:187], v162 offset:16384
	ds_read_b128 v[188:191], v162 offset:17408
	ds_read_b128 v[192:195], v162 offset:18432
	ds_read_b128 v[196:199], v162 offset:19456
	ds_read_b128 v[200:203], v162 offset:20480
	ds_read_b128 v[204:207], v162 offset:21504
	ds_read_b128 v[208:211], v162 offset:22528
	ds_read_b128 v[212:215], v162 offset:23552
	global_load_lds_dwordx4 v[158:159], off
	s_add_i32 m0, s67, 0x2000
	s_add_u32 s68, s50, 0x80000
	v_lshl_add_u64 v[216:217], s[50:51], 0, v[136:137]
	s_addc_u32 s69, s51, 0
	s_add_i32 s67, s57, s12
	global_load_lds_dwordx4 v[216:217], off
	v_lshl_add_u64 v[218:219], s[68:69], 0, v[132:133]
	s_mov_b32 m0, s67
	v_lshl_add_u64 v[220:221], s[52:53], 0, v[134:135]
	global_load_lds_dwordx4 v[218:219], off
	v_lshl_add_u64 v[218:219], s[68:69], 0, v[136:137]
	s_add_i32 m0, s67, 0x2000
	s_nop 0
	global_load_lds_dwordx4 v[218:219], off
	v_lshl_add_u64 v[218:219], s[52:53], 0, v[130:131]
	s_mov_b32 m0, s14
	s_nop 0
	global_load_lds_dwordx4 v[218:219], off
	s_mov_b32 m0, s15
	s_nop 0
	global_load_lds_dwordx4 v[220:221], off
	s_waitcnt vmcnt(8)
	s_waitcnt lgkmcnt(0)
	s_barrier
; #define PG8_STAGE(bufoff, gbase, voff) do { _Pragma("unroll") for (int _i = 0; _i < 2; ++_i) \
;         __builtin_amdgcn_global_load_lds((const unsigned*)((const char*)(gbase) + (voff)[_i]), (PG8_LAS unsigned*)(lds + (bufoff) + ldsw + _i * 8192), 16, 0, 0); } while (0)
; #define PG8_LDA(dst, b, h) do { _Pragma("unroll") for (int m = 0; m < 4; ++m) _Pragma("unroll") for (int k = 0; k < 2; ++k) dst[m][k] = *(const PG8_LAS bf16x8*)(lds + PG8_SA(b, h) + aoff + m * 2048 + k * 1024); } while (0)
; #define PG8_LDB(dst, b, h) do { _Pragma("unroll") for (int n = 0; n < 2; ++n) _Pragma("unroll") for (int k = 0; k < 2; ++k) dst[n][k] = *(const PG8_LAS bf16x8*)(lds + PG8_SB(b, h) + boff + n * 2048 + k * 1024); } while (0)
; #define PG8_MMA(ai, bj, At, Bt) do { __builtin_amdgcn_s_setprio(1); _Pragma("unroll") for (int m = 0; m < 4; ++m) _Pragma("unroll") for (int n = 0; n < 2; ++n) _Pragma("unroll") for (int k = 0; k < 2; ++k) \
;         acc[ai][bj][m][n] = __builtin_amdgcn_mfma_f32_16x16x32_bf16(Bt[n][k], At[m][k], acc[ai][bj][m][n], 0, 0, 0); __builtin_amdgcn_s_setprio(0); } while (0)
; #define PG8_WAIT_V(n) asm volatile("s_waitcnt vmcnt(" #n ")" ::: "memory")
; #define PG8_WAIT_L(n) asm volatile("s_waitcnt lgkmcnt(" #n ")" ::: "memory")
; #define PG8_BAR __builtin_amdgcn_s_barrier()
; #define PG8_SCHED __builtin_amdgcn_sched_barrier(0)
; template <class Epi, class Sched, bool ALIGN_EPI>
; __device__ __forceinline__ unsigned long long gemm_phase(PG8_LAS unsigned char* lds, const Gemm g, const Sched& S, const Epi& E, const int probe_id) {
;     ...
;             PG8_WAIT_V(8); PG8_WAIT_L(0); PG8_BAR; PG8_MMA(1, 0, At, B0); PG8_MMA(1, 1, At, B1); PG8_BAR; PG8_SCHED;
;             PG8_LDB(B0, 1, 0); PG8_LDB(B1, 1, 1); PG8_SCHED; PG8_LDA(At, 1, 0); PG8_STAGE(PG8_SA(0, 1), a2 + hstepA, voffA);
;             PG8_WAIT_V(8); PG8_WAIT_L(0); PG8_BAR; PG8_MMA(0, 0, At, B0); PG8_MMA(0, 1, At, B1); PG8_BAR; PG8_SCHED;
	s_setprio 1
	s_waitcnt lgkmcnt(0)
	v_mfma_f32_16x16x32_bf16 v[62:65], v[146:149], v[184:187], v[62:65]
	v_mfma_f32_16x16x32_bf16 v[58:61], v[154:157], v[184:187], v[58:61]
	v_mfma_f32_16x16x32_bf16 v[54:57], v[146:149], v[192:195], v[54:57]
	v_mfma_f32_16x16x32_bf16 v[50:53], v[154:157], v[192:195], v[50:53]
	v_mfma_f32_16x16x32_bf16 v[46:49], v[146:149], v[200:203], v[46:49]
	v_mfma_f32_16x16x32_bf16 v[42:45], v[154:157], v[200:203], v[42:45]
	v_mfma_f32_16x16x32_bf16 v[38:41], v[146:149], v[208:211], v[38:41]
	v_mfma_f32_16x16x32_bf16 v[34:37], v[154:157], v[208:211], v[34:37]
	v_mfma_f32_16x16x32_bf16 v[62:65], v[150:153], v[188:191], v[62:65]
	v_mfma_f32_16x16x32_bf16 v[58:61], v[164:167], v[188:191], v[58:61]
	v_mfma_f32_16x16x32_bf16 v[54:57], v[150:153], v[196:199], v[54:57]
	v_mfma_f32_16x16x32_bf16 v[50:53], v[164:167], v[196:199], v[50:53]
	v_mfma_f32_16x16x32_bf16 v[46:49], v[150:153], v[204:207], v[46:49]
	v_mfma_f32_16x16x32_bf16 v[42:45], v[164:167], v[204:207], v[42:45]
	v_mfma_f32_16x16x32_bf16 v[38:41], v[150:153], v[212:215], v[38:41]
	v_mfma_f32_16x16x32_bf16 v[34:37], v[164:167], v[212:215], v[34:37]
	s_setprio 0
	s_setprio 1
	v_mfma_f32_16x16x32_bf16 v[30:33], v[168:171], v[184:187], v[30:33]
	v_mfma_f32_16x16x32_bf16 v[26:29], v[176:179], v[184:187], v[26:29]
	v_mfma_f32_16x16x32_bf16 v[22:25], v[168:171], v[192:195], v[22:25]
	v_mfma_f32_16x16x32_bf16 v[18:21], v[176:179], v[192:195], v[18:21]
	v_mfma_f32_16x16x32_bf16 v[14:17], v[168:171], v[200:203], v[14:17]
	v_mfma_f32_16x16x32_bf16 v[10:13], v[176:179], v[200:203], v[10:13]
	v_mfma_f32_16x16x32_bf16 v[6:9], v[168:171], v[208:211], v[6:9]
	v_mfma_f32_16x16x32_bf16 v[2:5], v[176:179], v[208:211], v[2:5]
	v_mfma_f32_16x16x32_bf16 v[30:33], v[172:175], v[188:191], v[30:33]
	v_mfma_f32_16x16x32_bf16 v[26:29], v[180:183], v[188:191], v[26:29]
	v_mfma_f32_16x16x32_bf16 v[22:25], v[172:175], v[196:199], v[22:25]
	v_mfma_f32_16x16x32_bf16 v[18:21], v[180:183], v[196:199], v[18:21]
	v_mfma_f32_16x16x32_bf16 v[14:17], v[172:175], v[204:207], v[14:17]
	v_mfma_f32_16x16x32_bf16 v[10:13], v[180:183], v[204:207], v[10:13]
	v_mfma_f32_16x16x32_bf16 v[6:9], v[172:175], v[212:215], v[6:9]
	v_mfma_f32_16x16x32_bf16 v[2:5], v[180:183], v[212:215], v[2:5]
	s_setprio 0
	s_barrier
	s_add_i32 s67, 0, 0x18000
	v_add_u32_e32 v163, s67, v160
	s_add_i32 s68, 0, 0x1c000
	ds_read_b128 v[146:149], v163
	ds_read_b128 v[150:153], v163 offset:1024
	ds_read_b128 v[154:157], v163 offset:2048
	ds_read_b128 v[164:167], v163 offset:3072
	v_add_u32_e32 v163, s68, v160
	ds_read_b128 v[168:171], v163
	ds_read_b128 v[172:175], v163 offset:1024
	ds_read_b128 v[176:179], v163 offset:2048
	ds_read_b128 v[180:183], v163 offset:3072
	s_add_u32 s52, s52, 0x80000
	s_addc_u32 s53, s53, 0
	s_mov_b32 m0, s34
	v_lshl_add_u64 v[222:223], s[52:53], 0, v[130:131]
	ds_read_b128 v[184:187], v162 offset:32768
	ds_read_b128 v[188:191], v162 offset:33792
	ds_read_b128 v[192:195], v162 offset:34816
	ds_read_b128 v[196:199], v162 offset:35840
	ds_read_b128 v[200:203], v162 offset:36864
	ds_read_b128 v[204:207], v162 offset:37888
	ds_read_b128 v[208:211], v162 offset:38912
	ds_read_b128 v[212:215], v162 offset:39936
	global_load_lds_dwordx4 v[222:223], off
	v_lshl_add_u64 v[222:223], s[52:53], 0, v[134:135]
	s_mov_b32 m0, s35
	s_nop 0
	global_load_lds_dwordx4 v[222:223], off
	s_waitcnt vmcnt(8)
	s_waitcnt lgkmcnt(0)
	s_barrier
	s_setprio 1
	s_waitcnt lgkmcnt(0)
	v_mfma_f32_16x16x32_bf16 v[126:129], v[146:149], v[184:187], v[126:129]
	v_mfma_f32_16x16x32_bf16 v[122:125], v[154:157], v[184:187], v[122:125]
	v_mfma_f32_16x16x32_bf16 v[118:121], v[146:149], v[192:195], v[118:121]
	v_mfma_f32_16x16x32_bf16 v[114:117], v[154:157], v[192:195], v[114:117]
	v_mfma_f32_16x16x32_bf16 v[110:113], v[146:149], v[200:203], v[110:113]
	v_mfma_f32_16x16x32_bf16 v[106:109], v[154:157], v[200:203], v[106:109]
	v_mfma_f32_16x16x32_bf16 v[102:105], v[146:149], v[208:211], v[102:105]
	v_mfma_f32_16x16x32_bf16 v[98:101], v[154:157], v[208:211], v[98:101]
	v_mfma_f32_16x16x32_bf16 v[126:129], v[150:153], v[188:191], v[126:129]
	v_mfma_f32_16x16x32_bf16 v[122:125], v[164:167], v[188:191], v[122:125]
	v_mfma_f32_16x16x32_bf16 v[118:121], v[150:153], v[196:199], v[118:121]
	v_mfma_f32_16x16x32_bf16 v[114:117], v[164:167], v[196:199], v[114:117]
	v_mfma_f32_16x16x32_bf16 v[110:113], v[150:153], v[204:207], v[110:113]
	v_mfma_f32_16x16x32_bf16 v[106:109], v[164:167], v[204:207], v[106:109]
	v_mfma_f32_16x16x32_bf16 v[102:105], v[150:153], v[212:215], v[102:105]
	v_mfma_f32_16x16x32_bf16 v[98:101], v[164:167], v[212:215], v[98:101]
	s_setprio 0
	s_setprio 1
	v_mfma_f32_16x16x32_bf16 v[94:97], v[168:171], v[184:187], v[94:97]
	v_mfma_f32_16x16x32_bf16 v[90:93], v[176:179], v[184:187], v[90:93]
	v_mfma_f32_16x16x32_bf16 v[86:89], v[168:171], v[192:195], v[86:89]
	v_mfma_f32_16x16x32_bf16 v[82:85], v[176:179], v[192:195], v[82:85]
	v_mfma_f32_16x16x32_bf16 v[78:81], v[168:171], v[200:203], v[78:81]
	v_mfma_f32_16x16x32_bf16 v[74:77], v[176:179], v[200:203], v[74:77]
	v_mfma_f32_16x16x32_bf16 v[70:73], v[168:171], v[208:211], v[70:73]
	v_mfma_f32_16x16x32_bf16 v[66:69], v[176:179], v[208:211], v[66:69]
	v_mfma_f32_16x16x32_bf16 v[94:97], v[172:175], v[188:191], v[94:97]
	v_mfma_f32_16x16x32_bf16 v[90:93], v[180:183], v[188:191], v[90:93]
	v_mfma_f32_16x16x32_bf16 v[86:89], v[172:175], v[196:199], v[86:89]
	v_mfma_f32_16x16x32_bf16 v[82:85], v[180:183], v[196:199], v[82:85]
	v_mfma_f32_16x16x32_bf16 v[78:81], v[172:175], v[204:207], v[78:81]
	v_mfma_f32_16x16x32_bf16 v[74:77], v[180:183], v[204:207], v[74:77]
	v_mfma_f32_16x16x32_bf16 v[70:73], v[172:175], v[212:215], v[70:73]
	v_mfma_f32_16x16x32_bf16 v[66:69], v[180:183], v[212:215], v[66:69]
	s_setprio 0
	s_barrier
; #define PG8_STAGE(bufoff, gbase, voff) do { _Pragma("unroll") for (int _i = 0; _i < 2; ++_i) \
;         __builtin_amdgcn_global_load_lds((const unsigned*)((const char*)(gbase) + (voff)[_i]), (PG8_LAS unsigned*)(lds + (bufoff) + ldsw + _i * 8192), 16, 0, 0); } while (0)
; #define PG8_LDA(dst, b, h) do { _Pragma("unroll") for (int m = 0; m < 4; ++m) _Pragma("unroll") for (int k = 0; k < 2; ++k) dst[m][k] = *(const PG8_LAS bf16x8*)(lds + PG8_SA(b, h) + aoff + m * 2048 + k * 1024); } while (0)
; #define PG8_MMA(ai, bj, At, Bt) do { __builtin_amdgcn_s_setprio(1); _Pragma("unroll") for (int m = 0; m < 4; ++m) _Pragma("unroll") for (int n = 0; n < 2; ++n) _Pragma("unroll") for (int k = 0; k < 2; ++k) \
;         acc[ai][bj][m][n] = __builtin_amdgcn_mfma_f32_16x16x32_bf16(Bt[n][k], At[m][k], acc[ai][bj][m][n], 0, 0, 0); __builtin_amdgcn_s_setprio(0); } while (0)
; #define PG8_WAIT_V(n) asm volatile("s_waitcnt vmcnt(" #n ")" ::: "memory")
; #define PG8_WAIT_L(n) asm volatile("s_waitcnt lgkmcnt(" #n ")" ::: "memory")
; #define PG8_BAR __builtin_amdgcn_s_barrier()
; #define PG8_SCHED __builtin_amdgcn_sched_barrier(0)
; template <class Epi, class Sched, bool ALIGN_EPI>
; __device__ __forceinline__ unsigned long long gemm_phase(PG8_LAS unsigned char* lds, const Gemm g, const Sched& S, const Epi& E, const int probe_id) {
;     ...
;             PG8_LDA(At, 1, 1); PG8_STAGE(PG8_SB(1, 0), b3, voffB); PG8_STAGE(PG8_SB(1, 1), b3 + hstepB, voffB); PG8_STAGE(PG8_SA(1, 0), a3, voffA);
;             PG8_WAIT_V(8); PG8_WAIT_L(0); PG8_BAR; PG8_MMA(1, 0, At, B0); PG8_MMA(1, 1, At, B1); PG8_BAR; PG8_SCHED;
;         }
;     __device__ __forceinline__ bool operator()(pg8::f32x4 (&acc)[2][2][4][2], const pg8::Unit& u, int wr, int wc, int fr, int fq) const {
;         const int row0 = u.pm * 256 + wr * 64 + fr, col0 = u.pn * 256 + wc * 32 + 8 * fq;
;         v4u gA[2][2][2], gB[2][2][2];
;     ...
;         if (u.kp == 0) {
	s_add_i32 s52, s67, s12
	v_lshl_add_u64 v[158:159], v[158:159], 0, s[22:23]
	s_mov_b32 m0, s52
	ds_read_b128 v[184:187], v162 offset:49152
	ds_read_b128 v[188:191], v162 offset:50176
	ds_read_b128 v[192:195], v162 offset:51200
	ds_read_b128 v[196:199], v162 offset:52224
	ds_read_b128 v[200:203], v162 offset:53248
	ds_read_b128 v[204:207], v162 offset:54272
	ds_read_b128 v[208:211], v162 offset:55296
	ds_read_b128 v[212:215], v162 offset:56320
	global_load_lds_dwordx4 v[158:159], off
	s_add_i32 m0, s52, 0x2000
	s_add_u32 s50, s50, 0x80080
	v_lshl_add_u64 v[158:159], v[216:217], 0, s[22:23]
	s_addc_u32 s51, s51, 0
	s_add_i32 s52, s68, s12
	global_load_lds_dwordx4 v[158:159], off
	v_lshl_add_u64 v[158:159], s[50:51], 0, v[132:133]
	s_mov_b32 m0, s52
	s_nop 0
	global_load_lds_dwordx4 v[158:159], off
	v_lshl_add_u64 v[158:159], s[50:51], 0, v[136:137]
	s_add_i32 m0, s52, 0x2000
	s_nop 0
	global_load_lds_dwordx4 v[158:159], off
	v_lshl_add_u64 v[158:159], v[218:219], 0, s[22:23]
	s_mov_b32 m0, s54
	s_nop 0
	global_load_lds_dwordx4 v[158:159], off
	v_lshl_add_u64 v[158:159], v[220:221], 0, s[22:23]
	s_mov_b32 m0, s55
	s_nop 0
	global_load_lds_dwordx4 v[158:159], off
	s_waitcnt vmcnt(8)
	s_waitcnt lgkmcnt(0)
	s_barrier
	s_setprio 1
	s_waitcnt lgkmcnt(0)
	v_mfma_f32_16x16x32_bf16 v[62:65], v[146:149], v[184:187], v[62:65]
	v_mfma_f32_16x16x32_bf16 v[58:61], v[154:157], v[184:187], v[58:61]
	v_mfma_f32_16x16x32_bf16 v[54:57], v[146:149], v[192:195], v[54:57]
	v_mfma_f32_16x16x32_bf16 v[50:53], v[154:157], v[192:195], v[50:53]
	v_mfma_f32_16x16x32_bf16 v[46:49], v[146:149], v[200:203], v[46:49]
	v_mfma_f32_16x16x32_bf16 v[42:45], v[154:157], v[200:203], v[42:45]
	v_mfma_f32_16x16x32_bf16 v[38:41], v[146:149], v[208:211], v[38:41]
	v_mfma_f32_16x16x32_bf16 v[34:37], v[154:157], v[208:211], v[34:37]
	v_mfma_f32_16x16x32_bf16 v[62:65], v[150:153], v[188:191], v[62:65]
	v_mfma_f32_16x16x32_bf16 v[58:61], v[164:167], v[188:191], v[58:61]
	v_mfma_f32_16x16x32_bf16 v[54:57], v[150:153], v[196:199], v[54:57]
	v_mfma_f32_16x16x32_bf16 v[50:53], v[164:167], v[196:199], v[50:53]
	v_mfma_f32_16x16x32_bf16 v[46:49], v[150:153], v[204:207], v[46:49]
	v_mfma_f32_16x16x32_bf16 v[42:45], v[164:167], v[204:207], v[42:45]
	v_mfma_f32_16x16x32_bf16 v[38:41], v[150:153], v[212:215], v[38:41]
	v_mfma_f32_16x16x32_bf16 v[34:37], v[164:167], v[212:215], v[34:37]
	s_setprio 0
	s_setprio 1
	v_mfma_f32_16x16x32_bf16 v[30:33], v[168:171], v[184:187], v[30:33]
	v_mfma_f32_16x16x32_bf16 v[26:29], v[176:179], v[184:187], v[26:29]
	v_mfma_f32_16x16x32_bf16 v[22:25], v[168:171], v[192:195], v[22:25]
	v_mfma_f32_16x16x32_bf16 v[18:21], v[176:179], v[192:195], v[18:21]
	v_mfma_f32_16x16x32_bf16 v[14:17], v[168:171], v[200:203], v[14:17]
	v_mfma_f32_16x16x32_bf16 v[10:13], v[176:179], v[200:203], v[10:13]
	v_mfma_f32_16x16x32_bf16 v[6:9], v[168:171], v[208:211], v[6:9]
	v_mfma_f32_16x16x32_bf16 v[2:5], v[176:179], v[208:211], v[2:5]
	v_mfma_f32_16x16x32_bf16 v[30:33], v[172:175], v[188:191], v[30:33]
	v_mfma_f32_16x16x32_bf16 v[26:29], v[180:183], v[188:191], v[26:29]
	v_mfma_f32_16x16x32_bf16 v[22:25], v[172:175], v[196:199], v[22:25]
	v_mfma_f32_16x16x32_bf16 v[18:21], v[180:183], v[196:199], v[18:21]
	v_mfma_f32_16x16x32_bf16 v[14:17], v[172:175], v[204:207], v[14:17]
	v_mfma_f32_16x16x32_bf16 v[10:13], v[180:183], v[204:207], v[10:13]
	v_mfma_f32_16x16x32_bf16 v[6:9], v[172:175], v[212:215], v[6:9]
	v_mfma_f32_16x16x32_bf16 v[2:5], v[180:183], v[212:215], v[2:5]
	s_add_i32 s66, s66, 2
	s_add_u32 s48, s48, 0x100
	s_addc_u32 s49, s49, 0
	s_add_u32 s64, s64, 0x100
	s_addc_u32 s65, s65, 0
	s_cmp_gt_u32 s66, 13
	s_setprio 0
	s_barrier
	s_cbranch_scc0 .LBB0_621
	v_lshl_add_u32 v146, s46, 8, v1
	v_or_b32_e32 v152, 16, v146
	v_or_b32_e32 v154, 32, v146
	v_or_b32_e32 v156, 48, v146
	v_lshl_or_b32 v148, s47, 8, v161
	s_cmp_lg_u32 s2, 0
	v_ashrrev_i32_e32 v147, 31, v146
	v_ashrrev_i32_e32 v153, 31, v152
	v_ashrrev_i32_e32 v155, 31, v154
	v_ashrrev_i32_e32 v157, 31, v156
	s_cselect_b64 s[46:47], -1, 0
	s_cmp_eq_u32 s2, 0
	v_ashrrev_i32_e32 v149, 31, v148
	v_lshlrev_b64 v[150:151], 11, v[146:147]
	v_lshlrev_b64 v[152:153], 11, v[152:153]
	v_lshlrev_b64 v[154:155], 11, v[154:155]
	v_lshlrev_b64 v[156:157], 11, v[156:157]
	s_cbranch_scc1 .LBB0_628
; #define GAS __attribute__((address_space(1)))
; __device__ __forceinline__ v4u pack8(const float* v) { v4u w; w.x = pk2(v[0], v[1]); w.y = pk2(v[2], v[3]); w.z = pk2(v[4], v[5]); w.w = pk2(v[6], v[7]); return w; }
; #define LOADG(P, G, buf, q) do { _Pragma("unroll") for (int m = 0; m < 2; ++m) _Pragma("unroll") for (int bj = 0; bj < 2; ++bj) \
;             G[buf][m][bj] = *(const GAS v4u*)((P) + (size_t)(row0 + ((q) >> 1) * 128 + (2 * ((q) & 1) + m) * 16) * DM + col0 + bj * 128); } while (0)
; #define GV(e) ((e) & 1 ? bfhi(w_[(e) >> 1]) : bflo(w_[(e) >> 1]))
;     __device__ __forceinline__ bool operator()(pg8::f32x4 (&acc)[2][2][4][2], const pg8::Unit& u, int wr, int wc, int fr, int fq) const {
;     ...
;         LOADG(GB, gB, 0, 0); __builtin_amdgcn_sched_barrier(0);
; #pragma unroll
;         for (int q = 0; q < 4; ++q) { const int ai = q >> 1, mh = q & 1, cb_ = q & 1;
;             if (q + 1 < 4) LOADG(GB, gB, cb_ ^ 1, q + 1);
;             __builtin_amdgcn_sched_barrier(0);
; #pragma unroll
;             for (int m = 0; m < 2; ++m)
; #pragma unroll
;                 for (int bj = 0; bj < 2; ++bj) { const unsigned w_[4] = {gB[cb_][m][bj].x, gB[cb_][m][bj].y, gB[cb_][m][bj].z, gB[cb_][m][bj].w};
;                     float v[8];
; #pragma unroll
;                     for (int e = 0; e < 8; ++e) v[e] = acc[ai][bj][2 * mh + m][e >> 2][e & 3] * GV(e);
;                     *(GAS v4u*)(MB + (size_t)(row0 + ai * 128 + (2 * mh + m) * 16) * DM + col0 + bj * 128) = pack8(v); }
	v_lshlrev_b64 v[158:159], 1, v[148:149]
	v_lshl_add_u64 v[196:197], s[10:11], 0, v[158:159]
	v_lshl_add_u64 v[168:169], v[196:197], 0, v[150:151]
	v_lshl_add_u64 v[176:177], v[196:197], 0, v[152:153]
	global_load_dwordx4 v[164:167], v[168:169], off
	s_nop 0
	global_load_dwordx4 v[168:171], v[168:169], off offset:256
	s_nop 0
	global_load_dwordx4 v[172:175], v[176:177], off
	s_nop 0
	global_load_dwordx4 v[176:179], v[176:177], off offset:256
	v_lshl_add_u64 v[184:185], v[196:197], 0, v[154:155]
	v_lshl_add_u64 v[192:193], v[196:197], 0, v[156:157]
	global_load_dwordx4 v[180:183], v[184:185], off
	s_nop 0
	global_load_dwordx4 v[184:187], v[184:185], off offset:256
	s_nop 0
	global_load_dwordx4 v[188:191], v[192:193], off
	s_nop 0
	global_load_dwordx4 v[192:195], v[192:193], off offset:256
	s_waitcnt vmcnt(0)
	v_lshlrev_b32_e32 v163, 16, v164
	v_and_b32_e32 v164, 0xffff0000, v164
	v_lshlrev_b32_e32 v198, 16, v165
	v_and_b32_e32 v165, 0xffff0000, v165
	v_lshlrev_b32_e32 v199, 16, v166
	v_and_b32_e32 v166, 0xffff0000, v166
	v_mul_f32_e32 v164, v127, v164
	v_mul_f32_e32 v198, v128, v198
	v_mul_f32_e32 v165, v129, v165
	v_mul_f32_e32 v199, v122, v199
	v_mul_f32_e32 v166, v123, v166
	v_lshlrev_b32_e32 v200, 16, v167
	v_and_b32_e32 v167, 0xffff0000, v167
	v_mul_f32_e32 v163, v126, v163
	v_mul_f32_e32 v167, v125, v167
	v_cvt_pk_bf16_f32 v164, v163, v164
	v_cvt_pk_bf16_f32 v165, v198, v165
	v_cvt_pk_bf16_f32 v166, v199, v166
	v_lshl_add_u64 v[198:199], s[20:21], 0, v[150:151]
	v_mul_f32_e32 v200, v124, v200
	v_cvt_pk_bf16_f32 v167, v200, v167
	v_lshl_add_u64 v[198:199], v[198:199], 0, v[158:159]
	global_store_dwordx4 v[198:199], v[164:167], off
	v_lshlrev_b32_e32 v163, 16, v168
	v_mul_f32_e32 v163, v94, v163
	v_and_b32_e32 v164, 0xffff0000, v168
	v_lshlrev_b32_e32 v165, 16, v169
	v_and_b32_e32 v166, 0xffff0000, v169
	v_lshlrev_b32_e32 v167, 16, v170
	v_mul_f32_e32 v164, v95, v164
	v_mul_f32_e32 v165, v96, v165
	v_mul_f32_e32 v166, v97, v166
	v_mul_f32_e32 v167, v90, v167
	v_and_b32_e32 v168, 0xffff0000, v170
	v_lshlrev_b32_e32 v169, 16, v171
	v_and_b32_e32 v170, 0xffff0000, v171
	v_mul_f32_e32 v168, v91, v168
	v_mul_f32_e32 v169, v92, v169
	v_mul_f32_e32 v170, v93, v170
	v_cvt_pk_bf16_f32 v164, v163, v164
	v_cvt_pk_bf16_f32 v165, v165, v166
	v_cvt_pk_bf16_f32 v166, v167, v168
	v_cvt_pk_bf16_f32 v167, v169, v170
	global_store_dwordx4 v[198:199], v[164:167], off offset:256
	v_and_b32_e32 v168, 0xffff0000, v174
	v_lshlrev_b32_e32 v169, 16, v175
	v_and_b32_e32 v164, 0xffff0000, v172
	v_lshlrev_b32_e32 v165, 16, v173
	v_and_b32_e32 v166, 0xffff0000, v173
	v_lshlrev_b32_e32 v167, 16, v174
	v_lshlrev_b32_e32 v163, 16, v172
	v_mul_f32_e32 v164, v119, v164
	v_mul_f32_e32 v165, v120, v165
	v_mul_f32_e32 v166, v121, v166
	v_mul_f32_e32 v167, v114, v167
	v_mul_f32_e32 v168, v115, v168
	v_mul_f32_e32 v169, v116, v169
	v_and_b32_e32 v170, 0xffff0000, v175
	v_mul_f32_e32 v163, v118, v163
	v_mul_f32_e32 v170, v117, v170
	v_cvt_pk_bf16_f32 v164, v163, v164
	v_cvt_pk_bf16_f32 v165, v165, v166
	v_cvt_pk_bf16_f32 v166, v167, v168
	v_cvt_pk_bf16_f32 v167, v169, v170
	v_lshl_add_u64 v[168:169], s[20:21], 0, v[152:153]
	v_lshl_add_u64 v[168:169], v[168:169], 0, v[158:159]
	global_store_dwordx4 v[168:169], v[164:167], off
	v_lshlrev_b32_e32 v163, 16, v176
	v_and_b32_e32 v170, 0xffff0000, v178
	v_and_b32_e32 v164, 0xffff0000, v176
	v_lshlrev_b32_e32 v165, 16, v177
	v_and_b32_e32 v166, 0xffff0000, v177
	v_lshlrev_b32_e32 v167, 16, v178
	v_mul_f32_e32 v164, v87, v164
	v_mul_f32_e32 v165, v88, v165
	v_mul_f32_e32 v166, v89, v166
	v_mul_f32_e32 v167, v82, v167
	v_lshlrev_b32_e32 v171, 16, v179
	v_and_b32_e32 v172, 0xffff0000, v179
	v_mul_f32_e32 v163, v86, v163
	v_mul_f32_e32 v170, v83, v170
	v_mul_f32_e32 v171, v84, v171
	v_mul_f32_e32 v172, v85, v172
	v_cvt_pk_bf16_f32 v164, v163, v164
	v_cvt_pk_bf16_f32 v165, v165, v166
	v_cvt_pk_bf16_f32 v166, v167, v170
	v_cvt_pk_bf16_f32 v167, v171, v172
	global_store_dwordx4 v[168:169], v[164:167], off offset:256
	v_lshl_add_u64 v[198:199], v[150:151], 0, s[24:25]
	v_lshl_add_u64 v[200:201], v[150:151], 0, s[26:27]
	v_lshl_add_u64 v[168:169], v[196:197], 0, v[198:199]
	v_lshl_add_u64 v[176:177], v[196:197], 0, v[200:201]
	global_load_dwordx4 v[164:167], v[168:169], off
	s_nop 0
	global_load_dwordx4 v[168:171], v[168:169], off offset:256
	s_nop 0
	global_load_dwordx4 v[172:175], v[176:177], off
	s_nop 0
	global_load_dwordx4 v[176:179], v[176:177], off offset:256
	v_lshlrev_b32_e32 v163, 16, v180
	v_and_b32_e32 v180, 0xffff0000, v180
	v_lshlrev_b32_e32 v202, 16, v181
	v_and_b32_e32 v181, 0xffff0000, v181
	v_lshlrev_b32_e32 v203, 16, v182
	v_and_b32_e32 v182, 0xffff0000, v182
	v_mul_f32_e32 v180, v111, v180
	v_mul_f32_e32 v202, v112, v202
	v_mul_f32_e32 v181, v113, v181
	v_mul_f32_e32 v203, v106, v203
	v_mul_f32_e32 v182, v107, v182
	v_lshlrev_b32_e32 v204, 16, v183
	v_and_b32_e32 v183, 0xffff0000, v183
	v_mul_f32_e32 v163, v110, v163
	v_mul_f32_e32 v183, v109, v183
	v_cvt_pk_bf16_f32 v180, v163, v180
	v_cvt_pk_bf16_f32 v181, v202, v181
	v_cvt_pk_bf16_f32 v182, v203, v182
	v_lshl_add_u64 v[202:203], s[20:21], 0, v[154:155]
	v_mul_f32_e32 v204, v108, v204
	v_cvt_pk_bf16_f32 v183, v204, v183
	v_lshl_add_u64 v[202:203], v[202:203], 0, v[158:159]
	global_store_dwordx4 v[202:203], v[180:183], off
	v_lshlrev_b32_e32 v163, 16, v184
	v_mul_f32_e32 v163, v78, v163
	v_and_b32_e32 v180, 0xffff0000, v184
	v_lshlrev_b32_e32 v181, 16, v185
	v_and_b32_e32 v182, 0xffff0000, v185
	v_lshlrev_b32_e32 v183, 16, v186
	v_mul_f32_e32 v180, v79, v180
	v_mul_f32_e32 v181, v80, v181
	v_mul_f32_e32 v182, v81, v182
	v_mul_f32_e32 v183, v74, v183
; #define GAS __attribute__((address_space(1)))
; __device__ __forceinline__ v4u pack8(const float* v) { v4u w; w.x = pk2(v[0], v[1]); w.y = pk2(v[2], v[3]); w.z = pk2(v[4], v[5]); w.w = pk2(v[6], v[7]); return w; }
; #define LOADG(P, G, buf, q) do { _Pragma("unroll") for (int m = 0; m < 2; ++m) _Pragma("unroll") for (int bj = 0; bj < 2; ++bj) \
;             G[buf][m][bj] = *(const GAS v4u*)((P) + (size_t)(row0 + ((q) >> 1) * 128 + (2 * ((q) & 1) + m) * 16) * DM + col0 + bj * 128); } while (0)
; #define GV(e) ((e) & 1 ? bfhi(w_[(e) >> 1]) : bflo(w_[(e) >> 1]))
;     __device__ __forceinline__ bool operator()(pg8::f32x4 (&acc)[2][2][4][2], const pg8::Unit& u, int wr, int wc, int fr, int fq) const {
;     ...
;         LOADG(GB, gB, 0, 0); __builtin_amdgcn_sched_barrier(0);
; #pragma unroll
;         for (int q = 0; q < 4; ++q) { const int ai = q >> 1, mh = q & 1, cb_ = q & 1;
;             if (q + 1 < 4) LOADG(GB, gB, cb_ ^ 1, q + 1);
;             __builtin_amdgcn_sched_barrier(0);
; #pragma unroll
;             for (int m = 0; m < 2; ++m)
; #pragma unroll
;                 for (int bj = 0; bj < 2; ++bj) { const unsigned w_[4] = {gB[cb_][m][bj].x, gB[cb_][m][bj].y, gB[cb_][m][bj].z, gB[cb_][m][bj].w};
;                     float v[8];
; #pragma unroll
;                     for (int e = 0; e < 8; ++e) v[e] = acc[ai][bj][2 * mh + m][e >> 2][e & 3] * GV(e);
;                     *(GAS v4u*)(MB + (size_t)(row0 + ai * 128 + (2 * mh + m) * 16) * DM + col0 + bj * 128) = pack8(v); }
	v_and_b32_e32 v184, 0xffff0000, v186
	v_lshlrev_b32_e32 v185, 16, v187
	v_and_b32_e32 v186, 0xffff0000, v187
	v_mul_f32_e32 v184, v75, v184
	v_mul_f32_e32 v185, v76, v185
	v_mul_f32_e32 v186, v77, v186
	v_cvt_pk_bf16_f32 v180, v163, v180
	v_cvt_pk_bf16_f32 v181, v181, v182
	v_cvt_pk_bf16_f32 v182, v183, v184
	v_cvt_pk_bf16_f32 v183, v185, v186
	global_store_dwordx4 v[202:203], v[180:183], off offset:256
	v_and_b32_e32 v184, 0xffff0000, v190
	v_lshlrev_b32_e32 v185, 16, v191
	v_and_b32_e32 v180, 0xffff0000, v188
	v_lshlrev_b32_e32 v181, 16, v189
	v_and_b32_e32 v182, 0xffff0000, v189
	v_lshlrev_b32_e32 v183, 16, v190
	v_lshlrev_b32_e32 v163, 16, v188
	v_mul_f32_e32 v180, v103, v180
	v_mul_f32_e32 v181, v104, v181
	v_mul_f32_e32 v182, v105, v182
	v_mul_f32_e32 v183, v98, v183
	v_mul_f32_e32 v184, v99, v184
	v_mul_f32_e32 v185, v100, v185
	v_and_b32_e32 v186, 0xffff0000, v191
	v_mul_f32_e32 v163, v102, v163
	v_mul_f32_e32 v186, v101, v186
	v_cvt_pk_bf16_f32 v180, v163, v180
	v_cvt_pk_bf16_f32 v181, v181, v182
	v_cvt_pk_bf16_f32 v182, v183, v184
	v_cvt_pk_bf16_f32 v183, v185, v186
	v_lshl_add_u64 v[184:185], s[20:21], 0, v[156:157]
	v_lshl_add_u64 v[184:185], v[184:185], 0, v[158:159]
	global_store_dwordx4 v[184:185], v[180:183], off
	v_lshlrev_b32_e32 v163, 16, v192
	v_and_b32_e32 v186, 0xffff0000, v194
	v_and_b32_e32 v180, 0xffff0000, v192
	v_lshlrev_b32_e32 v181, 16, v193
	v_and_b32_e32 v182, 0xffff0000, v193
	v_lshlrev_b32_e32 v183, 16, v194
	v_mul_f32_e32 v180, v71, v180
	v_mul_f32_e32 v181, v72, v181
	v_mul_f32_e32 v182, v73, v182
	v_mul_f32_e32 v183, v66, v183
	v_lshlrev_b32_e32 v187, 16, v195
	v_and_b32_e32 v188, 0xffff0000, v195
	v_mul_f32_e32 v163, v70, v163
	v_mul_f32_e32 v186, v67, v186
	v_mul_f32_e32 v187, v68, v187
	v_mul_f32_e32 v188, v69, v188
	v_cvt_pk_bf16_f32 v180, v163, v180
	v_cvt_pk_bf16_f32 v181, v181, v182
	v_cvt_pk_bf16_f32 v182, v183, v186
	v_cvt_pk_bf16_f32 v183, v187, v188
	global_store_dwordx4 v[184:185], v[180:183], off offset:256
	s_nop 1
	v_add_u32_e32 v180, 0xa0, v146
	v_ashrrev_i32_e32 v181, 31, v180
	v_lshlrev_b64 v[202:203], 11, v[180:181]
	v_lshl_add_u64 v[204:205], v[150:151], 0, s[28:29]
	v_lshl_add_u64 v[184:185], v[196:197], 0, v[202:203]
	v_lshl_add_u64 v[192:193], v[196:197], 0, v[204:205]
	global_load_dwordx4 v[180:183], v[184:185], off
	s_nop 0
	global_load_dwordx4 v[184:187], v[184:185], off offset:256
	s_nop 0
	global_load_dwordx4 v[188:191], v[192:193], off
	s_nop 0
	global_load_dwordx4 v[192:195], v[192:193], off offset:256
	s_waitcnt vmcnt(11)
	v_lshlrev_b32_e32 v163, 16, v164
	v_and_b32_e32 v164, 0xffff0000, v164
	v_lshlrev_b32_e32 v196, 16, v165
	v_and_b32_e32 v165, 0xffff0000, v165
	v_lshlrev_b32_e32 v197, 16, v166
	v_and_b32_e32 v166, 0xffff0000, v166
	v_mul_f32_e32 v164, v63, v164
	v_mul_f32_e32 v196, v64, v196
	v_mul_f32_e32 v165, v65, v165
	v_mul_f32_e32 v197, v58, v197
	v_mul_f32_e32 v166, v59, v166
	v_lshlrev_b32_e32 v206, 16, v167
	v_and_b32_e32 v167, 0xffff0000, v167
	v_mul_f32_e32 v163, v62, v163
	v_mul_f32_e32 v167, v61, v167
	v_cvt_pk_bf16_f32 v164, v163, v164
	v_cvt_pk_bf16_f32 v165, v196, v165
	v_cvt_pk_bf16_f32 v166, v197, v166
	v_lshl_add_u64 v[196:197], s[20:21], 0, v[198:199]
	v_mul_f32_e32 v206, v60, v206
	v_cvt_pk_bf16_f32 v167, v206, v167
	v_lshl_add_u64 v[196:197], v[196:197], 0, v[158:159]
	global_store_dwordx4 v[196:197], v[164:167], off
	s_waitcnt vmcnt(11)
	v_lshlrev_b32_e32 v163, 16, v168
	v_mul_f32_e32 v163, v30, v163
	v_and_b32_e32 v164, 0xffff0000, v168
	v_lshlrev_b32_e32 v165, 16, v169
	v_and_b32_e32 v166, 0xffff0000, v169
	v_lshlrev_b32_e32 v167, 16, v170
	v_mul_f32_e32 v164, v31, v164
	v_mul_f32_e32 v165, v32, v165
	v_mul_f32_e32 v166, v33, v166
	v_mul_f32_e32 v167, v26, v167
	v_and_b32_e32 v168, 0xffff0000, v170
	v_lshlrev_b32_e32 v169, 16, v171
	v_and_b32_e32 v170, 0xffff0000, v171
	v_mul_f32_e32 v168, v27, v168
	v_mul_f32_e32 v169, v28, v169
	v_mul_f32_e32 v170, v29, v170
	v_cvt_pk_bf16_f32 v164, v163, v164
	v_cvt_pk_bf16_f32 v165, v165, v166
	v_cvt_pk_bf16_f32 v166, v167, v168
	v_cvt_pk_bf16_f32 v167, v169, v170
	global_store_dwordx4 v[196:197], v[164:167], off offset:256
	s_waitcnt vmcnt(11)
; #define GAS __attribute__((address_space(1)))
; __device__ __forceinline__ v4u pack8(const float* v) { v4u w; w.x = pk2(v[0], v[1]); w.y = pk2(v[2], v[3]); w.z = pk2(v[4], v[5]); w.w = pk2(v[6], v[7]); return w; }
; #define LOADG(P, G, buf, q) do { _Pragma("unroll") for (int m = 0; m < 2; ++m) _Pragma("unroll") for (int bj = 0; bj < 2; ++bj) \
;             G[buf][m][bj] = *(const GAS v4u*)((P) + (size_t)(row0 + ((q) >> 1) * 128 + (2 * ((q) & 1) + m) * 16) * DM + col0 + bj * 128); } while (0)
; #define GV(e) ((e) & 1 ? bfhi(w_[(e) >> 1]) : bflo(w_[(e) >> 1]))
;     __device__ __forceinline__ bool operator()(pg8::f32x4 (&acc)[2][2][4][2], const pg8::Unit& u, int wr, int wc, int fr, int fq) const {
;     ...
;         LOADG(GB, gB, 0, 0); __builtin_amdgcn_sched_barrier(0);
; #pragma unroll
;         for (int q = 0; q < 4; ++q) { const int ai = q >> 1, mh = q & 1, cb_ = q & 1;
;             if (q + 1 < 4) LOADG(GB, gB, cb_ ^ 1, q + 1);
;             __builtin_amdgcn_sched_barrier(0);
; #pragma unroll
;             for (int m = 0; m < 2; ++m)
; #pragma unroll
;                 for (int bj = 0; bj < 2; ++bj) { const unsigned w_[4] = {gB[cb_][m][bj].x, gB[cb_][m][bj].y, gB[cb_][m][bj].z, gB[cb_][m][bj].w};
;                     float v[8];
; #pragma unroll
;                     for (int e = 0; e < 8; ++e) v[e] = acc[ai][bj][2 * mh + m][e >> 2][e & 3] * GV(e);
;                     *(GAS v4u*)(MB + (size_t)(row0 + ai * 128 + (2 * mh + m) * 16) * DM + col0 + bj * 128) = pack8(v); }
	v_and_b32_e32 v168, 0xffff0000, v174
	v_lshlrev_b32_e32 v169, 16, v175
	v_and_b32_e32 v164, 0xffff0000, v172
	v_lshlrev_b32_e32 v165, 16, v173
	v_and_b32_e32 v166, 0xffff0000, v173
	v_lshlrev_b32_e32 v167, 16, v174
	v_lshlrev_b32_e32 v163, 16, v172
	v_mul_f32_e32 v164, v55, v164
	v_mul_f32_e32 v165, v56, v165
	v_mul_f32_e32 v166, v57, v166
	v_mul_f32_e32 v167, v50, v167
	v_mul_f32_e32 v168, v51, v168
	v_mul_f32_e32 v169, v52, v169
	v_and_b32_e32 v170, 0xffff0000, v175
	v_mul_f32_e32 v163, v54, v163
	v_mul_f32_e32 v170, v53, v170
	v_cvt_pk_bf16_f32 v164, v163, v164
	v_cvt_pk_bf16_f32 v165, v165, v166
	v_cvt_pk_bf16_f32 v166, v167, v168
	v_cvt_pk_bf16_f32 v167, v169, v170
	v_lshl_add_u64 v[168:169], s[20:21], 0, v[200:201]
	v_lshl_add_u64 v[168:169], v[168:169], 0, v[158:159]
	global_store_dwordx4 v[168:169], v[164:167], off
	s_waitcnt vmcnt(11)
	v_lshlrev_b32_e32 v163, 16, v176
	v_and_b32_e32 v170, 0xffff0000, v178
	v_and_b32_e32 v164, 0xffff0000, v176
	v_lshlrev_b32_e32 v165, 16, v177
	v_and_b32_e32 v166, 0xffff0000, v177
	v_lshlrev_b32_e32 v167, 16, v178
	v_mul_f32_e32 v164, v23, v164
	v_mul_f32_e32 v165, v24, v165
	v_mul_f32_e32 v166, v25, v166
	v_mul_f32_e32 v167, v18, v167
	v_lshlrev_b32_e32 v171, 16, v179
	v_and_b32_e32 v172, 0xffff0000, v179
	v_mul_f32_e32 v163, v22, v163
	v_mul_f32_e32 v170, v19, v170
	v_mul_f32_e32 v171, v20, v171
	v_mul_f32_e32 v172, v21, v172
	v_cvt_pk_bf16_f32 v164, v163, v164
	v_cvt_pk_bf16_f32 v165, v165, v166
	v_cvt_pk_bf16_f32 v166, v167, v170
	v_cvt_pk_bf16_f32 v167, v171, v172
	global_store_dwordx4 v[168:169], v[164:167], off offset:256
	s_waitcnt vmcnt(7)
	s_nop 0
	v_and_b32_e32 v164, 0xffff0000, v180
	v_lshlrev_b32_e32 v165, 16, v181
	v_and_b32_e32 v166, 0xffff0000, v181
	v_lshlrev_b32_e32 v167, 16, v182
	v_and_b32_e32 v168, 0xffff0000, v182
	v_lshlrev_b32_e32 v169, 16, v183
	v_lshlrev_b32_e32 v163, 16, v180
	v_mul_f32_e32 v164, v47, v164
	v_mul_f32_e32 v165, v48, v165
	v_mul_f32_e32 v166, v49, v166
	v_mul_f32_e32 v167, v42, v167
	v_mul_f32_e32 v168, v43, v168
	v_mul_f32_e32 v169, v44, v169
	v_and_b32_e32 v170, 0xffff0000, v183
	v_mul_f32_e32 v163, v46, v163
	v_mul_f32_e32 v170, v45, v170
	v_cvt_pk_bf16_f32 v164, v163, v164
	v_cvt_pk_bf16_f32 v165, v165, v166
	v_cvt_pk_bf16_f32 v166, v167, v168
	v_cvt_pk_bf16_f32 v167, v169, v170
	v_lshl_add_u64 v[168:169], s[20:21], 0, v[202:203]
	v_lshl_add_u64 v[168:169], v[168:169], 0, v[158:159]
	global_store_dwordx4 v[168:169], v[164:167], off
	s_waitcnt vmcnt(7)
	v_lshlrev_b32_e32 v163, 16, v184
	v_and_b32_e32 v170, 0xffff0000, v186
	v_and_b32_e32 v164, 0xffff0000, v184
	v_lshlrev_b32_e32 v165, 16, v185
	v_and_b32_e32 v166, 0xffff0000, v185
	v_lshlrev_b32_e32 v167, 16, v186
	v_mul_f32_e32 v164, v15, v164
	v_mul_f32_e32 v165, v16, v165
	v_mul_f32_e32 v166, v17, v166
	v_mul_f32_e32 v167, v10, v167
	v_lshlrev_b32_e32 v171, 16, v187
	v_and_b32_e32 v172, 0xffff0000, v187
	v_mul_f32_e32 v163, v14, v163
	v_mul_f32_e32 v170, v11, v170
	v_mul_f32_e32 v171, v12, v171
	v_mul_f32_e32 v172, v13, v172
	v_cvt_pk_bf16_f32 v164, v163, v164
	v_cvt_pk_bf16_f32 v165, v165, v166
	v_cvt_pk_bf16_f32 v166, v167, v170
	v_cvt_pk_bf16_f32 v167, v171, v172
	global_store_dwordx4 v[168:169], v[164:167], off offset:256
	s_waitcnt vmcnt(7)
	v_and_b32_e32 v168, 0xffff0000, v190
	v_lshlrev_b32_e32 v169, 16, v191
	v_and_b32_e32 v164, 0xffff0000, v188
	v_lshlrev_b32_e32 v165, 16, v189
	v_and_b32_e32 v166, 0xffff0000, v189
	v_lshlrev_b32_e32 v167, 16, v190
	v_lshlrev_b32_e32 v163, 16, v188
	v_mul_f32_e32 v164, v39, v164
	v_mul_f32_e32 v165, v40, v165
	v_mul_f32_e32 v166, v41, v166
	v_mul_f32_e32 v167, v34, v167
	v_mul_f32_e32 v168, v35, v168
	v_mul_f32_e32 v169, v36, v169
	v_and_b32_e32 v170, 0xffff0000, v191
	v_mul_f32_e32 v163, v38, v163
	v_mul_f32_e32 v170, v37, v170
	v_cvt_pk_bf16_f32 v164, v163, v164
	v_cvt_pk_bf16_f32 v165, v165, v166
	v_cvt_pk_bf16_f32 v166, v167, v168
	v_cvt_pk_bf16_f32 v167, v169, v170
	v_lshl_add_u64 v[168:169], s[20:21], 0, v[204:205]
	v_lshl_add_u64 v[158:159], v[168:169], 0, v[158:159]
	global_store_dwordx4 v[158:159], v[164:167], off
	s_waitcnt vmcnt(7)
	v_lshlrev_b32_e32 v163, 16, v192
	v_and_b32_e32 v168, 0xffff0000, v194
	v_and_b32_e32 v164, 0xffff0000, v192
	v_lshlrev_b32_e32 v165, 16, v193
	v_and_b32_e32 v166, 0xffff0000, v193
	v_lshlrev_b32_e32 v167, 16, v194
	v_mul_f32_e32 v164, v7, v164
	v_mul_f32_e32 v165, v8, v165
	v_mul_f32_e32 v166, v9, v166
	v_mul_f32_e32 v167, v2, v167
	v_lshlrev_b32_e32 v169, 16, v195
	v_and_b32_e32 v170, 0xffff0000, v195
	v_mul_f32_e32 v163, v6, v163
	v_mul_f32_e32 v168, v3, v168
	v_mul_f32_e32 v169, v4, v169
	v_mul_f32_e32 v170, v5, v170
	v_cvt_pk_bf16_f32 v164, v163, v164
	v_cvt_pk_bf16_f32 v165, v165, v166
	v_cvt_pk_bf16_f32 v166, v167, v168
	v_cvt_pk_bf16_f32 v167, v169, v170
	global_store_dwordx4 v[158:159], v[164:167], off offset:256
	s_cbranch_execnz .LBB0_625

; #define PG8_STAGE(bufoff, gbase, voff) do { _Pragma("unroll") for (int _i = 0; _i < 2; ++_i) \
;         __builtin_amdgcn_global_load_lds((const unsigned*)((const char*)(gbase) + (voff)[_i]), (PG8_LAS unsigned*)(lds + (bufoff) + ldsw + _i * 8192), 16, 0, 0); } while (0)
; #define PG8_LDA(dst, b, h) do { _Pragma("unroll") for (int m = 0; m < 4; ++m) _Pragma("unroll") for (int k = 0; k < 2; ++k) dst[m][k] = *(const PG8_LAS bf16x8*)(lds + PG8_SA(b, h) + aoff + m * 2048 + k * 1024); } while (0)
; #define PG8_LDB(dst, b, h) do { _Pragma("unroll") for (int n = 0; n < 2; ++n) _Pragma("unroll") for (int k = 0; k < 2; ++k) dst[n][k] = *(const PG8_LAS bf16x8*)(lds + PG8_SB(b, h) + boff + n * 2048 + k * 1024); } while (0)
; #define PG8_MMA(ai, bj, At, Bt) do { __builtin_amdgcn_s_setprio(1); _Pragma("unroll") for (int m = 0; m < 4; ++m) _Pragma("unroll") for (int n = 0; n < 2; ++n) _Pragma("unroll") for (int k = 0; k < 2; ++k) \
;         acc[ai][bj][m][n] = __builtin_amdgcn_mfma_f32_16x16x32_bf16(Bt[n][k], At[m][k], acc[ai][bj][m][n], 0, 0, 0); __builtin_amdgcn_s_setprio(0); } while (0)
; #define PG8_WAIT_V(n) asm volatile("s_waitcnt vmcnt(" #n ")" ::: "memory")
; #define PG8_WAIT_L(n) asm volatile("s_waitcnt lgkmcnt(" #n ")" ::: "memory")
; #define PG8_BAR __builtin_amdgcn_s_barrier()
; #define PG8_SCHED __builtin_amdgcn_sched_barrier(0)
; template <class Epi, class Sched, bool ALIGN_EPI>
; __device__ __forceinline__ unsigned long long gemm_phase(PG8_LAS unsigned char* lds, const Gemm g, const Sched& S, const Epi& E, const int probe_id) {
;     ...
;         for (int t = 0; t < nt; t += 2) {
;             const bool last = (t == nt - 2);
;             const char* a1 = cA + (size_t)(t + 1) * kstep;
;             const char* a2 = last ? nA : cA + (size_t)(t + 2) * kstep; const char* b2 = last ? nB : cB + (size_t)(t + 2) * kstep;
;             const char* a3 = a2 + kstep; const char* b3 = b2 + kstep;
;             PG8_LDB(B0, 0, 0); PG8_LDB(B1, 0, 1); PG8_SCHED; PG8_LDA(At, 0, 0); PG8_STAGE(PG8_SA(1, 1), a1 + hstepA, voffA);
;             PG8_WAIT_V(8); PG8_WAIT_L(0); PG8_BAR; PG8_MMA(0, 0, At, B0); PG8_MMA(0, 1, At, B1); PG8_BAR; PG8_SCHED;
;             PG8_LDA(At, 0, 1); PG8_STAGE(PG8_SB(0, 0), b2, voffB); PG8_STAGE(PG8_SB(0, 1), b2 + hstepB, voffB); PG8_STAGE(PG8_SA(0, 0), a2, voffA);
.LBB0_722:
	ds_read_b128 v[150:153], v146
	ds_read_b128 v[154:157], v146 offset:1024
	ds_read_b128 v[158:161], v146 offset:2048
	ds_read_b128 v[162:165], v146 offset:3072
	ds_read_b128 v[166:169], v147
	ds_read_b128 v[170:173], v147 offset:1024
	ds_read_b128 v[174:177], v147 offset:2048
	ds_read_b128 v[178:181], v147 offset:3072
	s_add_u32 s36, s34, 0xfffc0080
	s_addc_u32 s37, s35, -1
	s_cmp_eq_u32 s55, 12
	s_cselect_b32 s39, s25, s37
	s_cselect_b32 s38, s51, s36
	s_cselect_b32 s37, s23, s54
	s_cselect_b32 s36, s52, s53
	v_lshl_add_u64 v[142:143], s[34:35], 0, v[134:135]
	s_add_i32 m0, s31, 0xc000
	ds_read_b128 v[182:185], v148
	ds_read_b128 v[186:189], v148 offset:1024
	ds_read_b128 v[190:193], v148 offset:2048
	ds_read_b128 v[194:197], v148 offset:3072
	ds_read_b128 v[198:201], v148 offset:4096
	ds_read_b128 v[202:205], v148 offset:5120
	ds_read_b128 v[206:209], v148 offset:6144
	ds_read_b128 v[210:213], v148 offset:7168
	global_load_lds_dwordx4 v[142:143], off
	v_lshl_add_u64 v[142:143], s[34:35], 0, v[136:137]
	s_add_i32 m0, s31, 0xe000
	s_nop 0
	global_load_lds_dwordx4 v[142:143], off
	s_waitcnt vmcnt(8)
	s_waitcnt lgkmcnt(0)
	s_barrier
	s_setprio 1
	s_waitcnt lgkmcnt(0)
	v_mfma_f32_16x16x32_bf16 v[126:129], v[150:153], v[182:185], v[126:129]
	v_mfma_f32_16x16x32_bf16 v[122:125], v[158:161], v[182:185], v[122:125]
	v_mfma_f32_16x16x32_bf16 v[118:121], v[150:153], v[190:193], v[118:121]
	v_mfma_f32_16x16x32_bf16 v[110:113], v[158:161], v[190:193], v[110:113]
	v_mfma_f32_16x16x32_bf16 v[98:101], v[150:153], v[198:201], v[98:101]
	v_mfma_f32_16x16x32_bf16 v[90:93], v[158:161], v[198:201], v[90:93]
	v_mfma_f32_16x16x32_bf16 v[86:89], v[150:153], v[206:209], v[86:89]
	v_mfma_f32_16x16x32_bf16 v[78:81], v[158:161], v[206:209], v[78:81]
	v_mfma_f32_16x16x32_bf16 v[126:129], v[154:157], v[186:189], v[126:129]
	v_mfma_f32_16x16x32_bf16 v[122:125], v[162:165], v[186:189], v[122:125]
	v_mfma_f32_16x16x32_bf16 v[118:121], v[154:157], v[194:197], v[118:121]
	v_mfma_f32_16x16x32_bf16 v[110:113], v[162:165], v[194:197], v[110:113]
	v_mfma_f32_16x16x32_bf16 v[98:101], v[154:157], v[202:205], v[98:101]
	v_mfma_f32_16x16x32_bf16 v[90:93], v[162:165], v[202:205], v[90:93]
	v_mfma_f32_16x16x32_bf16 v[86:89], v[154:157], v[210:213], v[86:89]
	v_mfma_f32_16x16x32_bf16 v[78:81], v[162:165], v[210:213], v[78:81]
	s_setprio 0
	s_setprio 1
	v_mfma_f32_16x16x32_bf16 v[114:117], v[166:169], v[182:185], v[114:117]
	v_mfma_f32_16x16x32_bf16 v[106:109], v[174:177], v[182:185], v[106:109]
	v_mfma_f32_16x16x32_bf16 v[102:105], v[166:169], v[190:193], v[102:105]
	v_mfma_f32_16x16x32_bf16 v[94:97], v[174:177], v[190:193], v[94:97]
	v_mfma_f32_16x16x32_bf16 v[82:85], v[166:169], v[198:201], v[82:85]
	v_mfma_f32_16x16x32_bf16 v[74:77], v[174:177], v[198:201], v[74:77]
	v_mfma_f32_16x16x32_bf16 v[70:73], v[166:169], v[206:209], v[70:73]
	v_mfma_f32_16x16x32_bf16 v[66:69], v[174:177], v[206:209], v[66:69]
	v_mfma_f32_16x16x32_bf16 v[114:117], v[170:173], v[186:189], v[114:117]
	v_mfma_f32_16x16x32_bf16 v[106:109], v[178:181], v[186:189], v[106:109]
	v_mfma_f32_16x16x32_bf16 v[102:105], v[170:173], v[194:197], v[102:105]
	v_mfma_f32_16x16x32_bf16 v[94:97], v[178:181], v[194:197], v[94:97]
	v_mfma_f32_16x16x32_bf16 v[82:85], v[170:173], v[202:205], v[82:85]
	v_mfma_f32_16x16x32_bf16 v[74:77], v[178:181], v[202:205], v[74:77]
	v_mfma_f32_16x16x32_bf16 v[70:73], v[170:173], v[210:213], v[70:73]
	v_mfma_f32_16x16x32_bf16 v[66:69], v[178:181], v[210:213], v[66:69]
	s_setprio 0
	s_barrier
	s_add_i32 s56, s48, s3
	v_lshl_add_u64 v[142:143], s[36:37], 0, v[130:131]
	s_mov_b32 m0, s56
	ds_read_b128 v[182:185], v148 offset:16384
	ds_read_b128 v[186:189], v148 offset:17408
	ds_read_b128 v[190:193], v148 offset:18432
	ds_read_b128 v[194:197], v148 offset:19456
	ds_read_b128 v[198:201], v148 offset:20480
	ds_read_b128 v[202:205], v148 offset:21504
	ds_read_b128 v[206:209], v148 offset:22528
	ds_read_b128 v[210:213], v148 offset:23552
	global_load_lds_dwordx4 v[142:143], off
	s_add_i32 m0, s56, 0x2000
	s_add_u32 s56, s36, 0x40000
	v_lshl_add_u64 v[214:215], s[36:37], 0, v[132:133]
	s_addc_u32 s57, s37, 0
	s_add_i32 s58, s49, s3
	global_load_lds_dwordx4 v[214:215], off
	v_lshl_add_u64 v[216:217], s[56:57], 0, v[130:131]
	s_mov_b32 m0, s58
	v_lshl_add_u64 v[218:219], s[38:39], 0, v[132:133]
	global_load_lds_dwordx4 v[216:217], off
	v_lshl_add_u64 v[216:217], s[56:57], 0, v[132:133]
	s_add_i32 m0, s58, 0x2000
	s_nop 0
	global_load_lds_dwordx4 v[216:217], off
	v_lshl_add_u64 v[216:217], s[38:39], 0, v[130:131]
	s_mov_b32 m0, s31
	s_nop 0
	global_load_lds_dwordx4 v[216:217], off
	s_mov_b32 m0, s41
	s_nop 0
	global_load_lds_dwordx4 v[218:219], off
	s_waitcnt vmcnt(8)
	s_waitcnt lgkmcnt(0)
	s_barrier
; #define PG8_STAGE(bufoff, gbase, voff) do { _Pragma("unroll") for (int _i = 0; _i < 2; ++_i) \
;         __builtin_amdgcn_global_load_lds((const unsigned*)((const char*)(gbase) + (voff)[_i]), (PG8_LAS unsigned*)(lds + (bufoff) + ldsw + _i * 8192), 16, 0, 0); } while (0)
; #define PG8_LDA(dst, b, h) do { _Pragma("unroll") for (int m = 0; m < 4; ++m) _Pragma("unroll") for (int k = 0; k < 2; ++k) dst[m][k] = *(const PG8_LAS bf16x8*)(lds + PG8_SA(b, h) + aoff + m * 2048 + k * 1024); } while (0)
; #define PG8_LDB(dst, b, h) do { _Pragma("unroll") for (int n = 0; n < 2; ++n) _Pragma("unroll") for (int k = 0; k < 2; ++k) dst[n][k] = *(const PG8_LAS bf16x8*)(lds + PG8_SB(b, h) + boff + n * 2048 + k * 1024); } while (0)
; #define PG8_MMA(ai, bj, At, Bt) do { __builtin_amdgcn_s_setprio(1); _Pragma("unroll") for (int m = 0; m < 4; ++m) _Pragma("unroll") for (int n = 0; n < 2; ++n) _Pragma("unroll") for (int k = 0; k < 2; ++k) \
;         acc[ai][bj][m][n] = __builtin_amdgcn_mfma_f32_16x16x32_bf16(Bt[n][k], At[m][k], acc[ai][bj][m][n], 0, 0, 0); __builtin_amdgcn_s_setprio(0); } while (0)
; #define PG8_WAIT_V(n) asm volatile("s_waitcnt vmcnt(" #n ")" ::: "memory")
; #define PG8_WAIT_L(n) asm volatile("s_waitcnt lgkmcnt(" #n ")" ::: "memory")
; #define PG8_BAR __builtin_amdgcn_s_barrier()
; #define PG8_SCHED __builtin_amdgcn_sched_barrier(0)
; template <class Epi, class Sched, bool ALIGN_EPI>
; __device__ __forceinline__ unsigned long long gemm_phase(PG8_LAS unsigned char* lds, const Gemm g, const Sched& S, const Epi& E, const int probe_id) {
;     ...
;             PG8_WAIT_V(8); PG8_WAIT_L(0); PG8_BAR; PG8_MMA(1, 0, At, B0); PG8_MMA(1, 1, At, B1); PG8_BAR; PG8_SCHED;
;             PG8_LDB(B0, 1, 0); PG8_LDB(B1, 1, 1); PG8_SCHED; PG8_LDA(At, 1, 0); PG8_STAGE(PG8_SA(0, 1), a2 + hstepA, voffA);
;             PG8_WAIT_V(8); PG8_WAIT_L(0); PG8_BAR; PG8_MMA(0, 0, At, B0); PG8_MMA(0, 1, At, B1); PG8_BAR; PG8_SCHED;
	s_setprio 1
	s_waitcnt lgkmcnt(0)
	v_mfma_f32_16x16x32_bf16 v[62:65], v[150:153], v[182:185], v[62:65]
	v_mfma_f32_16x16x32_bf16 v[58:61], v[158:161], v[182:185], v[58:61]
	v_mfma_f32_16x16x32_bf16 v[54:57], v[150:153], v[190:193], v[54:57]
	v_mfma_f32_16x16x32_bf16 v[46:49], v[158:161], v[190:193], v[46:49]
	v_mfma_f32_16x16x32_bf16 v[38:41], v[150:153], v[198:201], v[38:41]
	v_mfma_f32_16x16x32_bf16 v[26:29], v[158:161], v[198:201], v[26:29]
	v_mfma_f32_16x16x32_bf16 v[22:25], v[150:153], v[206:209], v[22:25]
	v_mfma_f32_16x16x32_bf16 v[14:17], v[158:161], v[206:209], v[14:17]
	v_mfma_f32_16x16x32_bf16 v[62:65], v[154:157], v[186:189], v[62:65]
	v_mfma_f32_16x16x32_bf16 v[58:61], v[162:165], v[186:189], v[58:61]
	v_mfma_f32_16x16x32_bf16 v[54:57], v[154:157], v[194:197], v[54:57]
	v_mfma_f32_16x16x32_bf16 v[46:49], v[162:165], v[194:197], v[46:49]
	v_mfma_f32_16x16x32_bf16 v[38:41], v[154:157], v[202:205], v[38:41]
	v_mfma_f32_16x16x32_bf16 v[26:29], v[162:165], v[202:205], v[26:29]
	v_mfma_f32_16x16x32_bf16 v[22:25], v[154:157], v[210:213], v[22:25]
	v_mfma_f32_16x16x32_bf16 v[14:17], v[162:165], v[210:213], v[14:17]
	s_setprio 0
	s_setprio 1
	v_mfma_f32_16x16x32_bf16 v[50:53], v[166:169], v[182:185], v[50:53]
	v_mfma_f32_16x16x32_bf16 v[42:45], v[174:177], v[182:185], v[42:45]
	v_mfma_f32_16x16x32_bf16 v[34:37], v[166:169], v[190:193], v[34:37]
	v_mfma_f32_16x16x32_bf16 v[30:33], v[174:177], v[190:193], v[30:33]
	v_mfma_f32_16x16x32_bf16 v[18:21], v[166:169], v[198:201], v[18:21]
	v_mfma_f32_16x16x32_bf16 v[10:13], v[174:177], v[198:201], v[10:13]
	v_mfma_f32_16x16x32_bf16 v[6:9], v[166:169], v[206:209], v[6:9]
	v_mfma_f32_16x16x32_bf16 v[2:5], v[174:177], v[206:209], v[2:5]
	v_mfma_f32_16x16x32_bf16 v[50:53], v[170:173], v[186:189], v[50:53]
	v_mfma_f32_16x16x32_bf16 v[42:45], v[178:181], v[186:189], v[42:45]
	v_mfma_f32_16x16x32_bf16 v[34:37], v[170:173], v[194:197], v[34:37]
	v_mfma_f32_16x16x32_bf16 v[30:33], v[178:181], v[194:197], v[30:33]
	v_mfma_f32_16x16x32_bf16 v[18:21], v[170:173], v[202:205], v[18:21]
	v_mfma_f32_16x16x32_bf16 v[10:13], v[178:181], v[202:205], v[10:13]
	v_mfma_f32_16x16x32_bf16 v[6:9], v[170:173], v[210:213], v[6:9]
	v_mfma_f32_16x16x32_bf16 v[2:5], v[178:181], v[210:213], v[2:5]
	s_setprio 0
	s_barrier
	s_add_i32 s56, 0, 0x18000
	v_add_u32_e32 v149, s56, v144
	s_add_i32 s57, 0, 0x1c000
	ds_read_b128 v[150:153], v149
	ds_read_b128 v[154:157], v149 offset:1024
	ds_read_b128 v[158:161], v149 offset:2048
	ds_read_b128 v[162:165], v149 offset:3072
	v_add_u32_e32 v149, s57, v144
	ds_read_b128 v[166:169], v149
	ds_read_b128 v[170:173], v149 offset:1024
	ds_read_b128 v[174:177], v149 offset:2048
	ds_read_b128 v[178:181], v149 offset:3072
	s_add_u32 s38, s38, 0x40000
	s_addc_u32 s39, s39, 0
	s_mov_b32 m0, s42
	v_lshl_add_u64 v[220:221], s[38:39], 0, v[130:131]
	ds_read_b128 v[182:185], v148 offset:32768
	ds_read_b128 v[186:189], v148 offset:33792
	ds_read_b128 v[190:193], v148 offset:34816
	ds_read_b128 v[194:197], v148 offset:35840
	ds_read_b128 v[198:201], v148 offset:36864
	ds_read_b128 v[202:205], v148 offset:37888
	ds_read_b128 v[206:209], v148 offset:38912
	ds_read_b128 v[210:213], v148 offset:39936
	global_load_lds_dwordx4 v[220:221], off
	v_lshl_add_u64 v[220:221], s[38:39], 0, v[132:133]
	s_mov_b32 m0, s43
	s_nop 0
	global_load_lds_dwordx4 v[220:221], off
	s_waitcnt vmcnt(8)
	s_waitcnt lgkmcnt(0)
	s_barrier
	s_setprio 1
	s_waitcnt lgkmcnt(0)
	v_mfma_f32_16x16x32_bf16 v[126:129], v[150:153], v[182:185], v[126:129]
	v_mfma_f32_16x16x32_bf16 v[122:125], v[158:161], v[182:185], v[122:125]
	v_mfma_f32_16x16x32_bf16 v[118:121], v[150:153], v[190:193], v[118:121]
	v_mfma_f32_16x16x32_bf16 v[110:113], v[158:161], v[190:193], v[110:113]
	v_mfma_f32_16x16x32_bf16 v[98:101], v[150:153], v[198:201], v[98:101]
	v_mfma_f32_16x16x32_bf16 v[90:93], v[158:161], v[198:201], v[90:93]
	v_mfma_f32_16x16x32_bf16 v[86:89], v[150:153], v[206:209], v[86:89]
	v_mfma_f32_16x16x32_bf16 v[78:81], v[158:161], v[206:209], v[78:81]
	v_mfma_f32_16x16x32_bf16 v[126:129], v[154:157], v[186:189], v[126:129]
	v_mfma_f32_16x16x32_bf16 v[122:125], v[162:165], v[186:189], v[122:125]
	v_mfma_f32_16x16x32_bf16 v[118:121], v[154:157], v[194:197], v[118:121]
	v_mfma_f32_16x16x32_bf16 v[110:113], v[162:165], v[194:197], v[110:113]
	v_mfma_f32_16x16x32_bf16 v[98:101], v[154:157], v[202:205], v[98:101]
	v_mfma_f32_16x16x32_bf16 v[90:93], v[162:165], v[202:205], v[90:93]
	v_mfma_f32_16x16x32_bf16 v[86:89], v[154:157], v[210:213], v[86:89]
	v_mfma_f32_16x16x32_bf16 v[78:81], v[162:165], v[210:213], v[78:81]
	s_setprio 0
	s_setprio 1
	v_mfma_f32_16x16x32_bf16 v[114:117], v[166:169], v[182:185], v[114:117]
	v_mfma_f32_16x16x32_bf16 v[106:109], v[174:177], v[182:185], v[106:109]
	v_mfma_f32_16x16x32_bf16 v[102:105], v[166:169], v[190:193], v[102:105]
	v_mfma_f32_16x16x32_bf16 v[94:97], v[174:177], v[190:193], v[94:97]
	v_mfma_f32_16x16x32_bf16 v[82:85], v[166:169], v[198:201], v[82:85]
	v_mfma_f32_16x16x32_bf16 v[74:77], v[174:177], v[198:201], v[74:77]
	v_mfma_f32_16x16x32_bf16 v[70:73], v[166:169], v[206:209], v[70:73]
	v_mfma_f32_16x16x32_bf16 v[66:69], v[174:177], v[206:209], v[66:69]
	v_mfma_f32_16x16x32_bf16 v[114:117], v[170:173], v[186:189], v[114:117]
	v_mfma_f32_16x16x32_bf16 v[106:109], v[178:181], v[186:189], v[106:109]
	v_mfma_f32_16x16x32_bf16 v[102:105], v[170:173], v[194:197], v[102:105]
	v_mfma_f32_16x16x32_bf16 v[94:97], v[178:181], v[194:197], v[94:97]
	v_mfma_f32_16x16x32_bf16 v[82:85], v[170:173], v[202:205], v[82:85]
	v_mfma_f32_16x16x32_bf16 v[74:77], v[178:181], v[202:205], v[74:77]
	v_mfma_f32_16x16x32_bf16 v[70:73], v[170:173], v[210:213], v[70:73]
	v_mfma_f32_16x16x32_bf16 v[66:69], v[178:181], v[210:213], v[66:69]
	s_setprio 0
	s_barrier
; #define PG8_STAGE(bufoff, gbase, voff) do { _Pragma("unroll") for (int _i = 0; _i < 2; ++_i) \
;         __builtin_amdgcn_global_load_lds((const unsigned*)((const char*)(gbase) + (voff)[_i]), (PG8_LAS unsigned*)(lds + (bufoff) + ldsw + _i * 8192), 16, 0, 0); } while (0)
; #define PG8_LDA(dst, b, h) do { _Pragma("unroll") for (int m = 0; m < 4; ++m) _Pragma("unroll") for (int k = 0; k < 2; ++k) dst[m][k] = *(const PG8_LAS bf16x8*)(lds + PG8_SA(b, h) + aoff + m * 2048 + k * 1024); } while (0)
; #define PG8_MMA(ai, bj, At, Bt) do { __builtin_amdgcn_s_setprio(1); _Pragma("unroll") for (int m = 0; m < 4; ++m) _Pragma("unroll") for (int n = 0; n < 2; ++n) _Pragma("unroll") for (int k = 0; k < 2; ++k) \
;         acc[ai][bj][m][n] = __builtin_amdgcn_mfma_f32_16x16x32_bf16(Bt[n][k], At[m][k], acc[ai][bj][m][n], 0, 0, 0); __builtin_amdgcn_s_setprio(0); } while (0)
; #define PG8_WAIT_V(n) asm volatile("s_waitcnt vmcnt(" #n ")" ::: "memory")
; #define PG8_WAIT_L(n) asm volatile("s_waitcnt lgkmcnt(" #n ")" ::: "memory")
; #define PG8_BAR __builtin_amdgcn_s_barrier()
; #define PG8_SCHED __builtin_amdgcn_sched_barrier(0)
; template <class Epi, class Sched, bool ALIGN_EPI>
; __device__ __forceinline__ unsigned long long gemm_phase(PG8_LAS unsigned char* lds, const Gemm g, const Sched& S, const Epi& E, const int probe_id) {
;     ...
;             PG8_LDA(At, 1, 1); PG8_STAGE(PG8_SB(1, 0), b3, voffB); PG8_STAGE(PG8_SB(1, 1), b3 + hstepB, voffB); PG8_STAGE(PG8_SA(1, 0), a3, voffA);
;             PG8_WAIT_V(8); PG8_WAIT_L(0); PG8_BAR; PG8_MMA(1, 0, At, B0); PG8_MMA(1, 1, At, B1); PG8_BAR; PG8_SCHED;
;         }
;     __device__ __forceinline__ bool operator()(pg8::f32x4 (&acc)[2][2][4][2], const pg8::Unit& u, int wr, int wc, int fr, int fq) const {
;         const int row0 = u.pm * 256 + wr * 64 + fr, col0 = u.pn * 256 + wc * 32 + 4 * fq;
;         const float* xb = (u.pm >= 256) ? xs - (size_t)MP * DM : xp;
;         f32x4 xv[2][2][2][2];
;     ...
;         LOADX(0, 0); __builtin_amdgcn_sched_barrier(0);
; #pragma unroll
;         for (int q = 0; q < 4; ++q) { const int ai = q >> 1, mh = q & 1, cb_ = q & 1;
;             if (q + 1 < 4) LOADX(cb_ ^ 1, q + 1);
	s_add_i32 s38, s56, s3
	v_lshl_add_u64 v[142:143], v[142:143], 0, s[10:11]
	s_mov_b32 m0, s38
	ds_read_b128 v[182:185], v148 offset:49152
	ds_read_b128 v[186:189], v148 offset:50176
	ds_read_b128 v[190:193], v148 offset:51200
	ds_read_b128 v[194:197], v148 offset:52224
	ds_read_b128 v[198:201], v148 offset:53248
	ds_read_b128 v[202:205], v148 offset:54272
	ds_read_b128 v[206:209], v148 offset:55296
	ds_read_b128 v[210:213], v148 offset:56320
	global_load_lds_dwordx4 v[142:143], off
	s_add_i32 m0, s38, 0x2000
	s_add_u32 s36, s36, 0x40080
	v_lshl_add_u64 v[142:143], v[214:215], 0, s[10:11]
	s_addc_u32 s37, s37, 0
	s_add_i32 s38, s57, s3
	global_load_lds_dwordx4 v[142:143], off
	v_lshl_add_u64 v[142:143], s[36:37], 0, v[130:131]
	s_mov_b32 m0, s38
	s_nop 0
	global_load_lds_dwordx4 v[142:143], off
	v_lshl_add_u64 v[142:143], s[36:37], 0, v[132:133]
	s_add_i32 m0, s38, 0x2000
	s_nop 0
	global_load_lds_dwordx4 v[142:143], off
	v_lshl_add_u64 v[142:143], v[216:217], 0, s[10:11]
	s_mov_b32 m0, s46
	s_nop 0
	global_load_lds_dwordx4 v[142:143], off
	v_lshl_add_u64 v[142:143], v[218:219], 0, s[10:11]
	s_mov_b32 m0, s47
	s_nop 0
	global_load_lds_dwordx4 v[142:143], off
	s_waitcnt vmcnt(8)
	s_waitcnt lgkmcnt(0)
	s_barrier
	s_setprio 1
	s_waitcnt lgkmcnt(0)
	v_mfma_f32_16x16x32_bf16 v[62:65], v[150:153], v[182:185], v[62:65]
	v_mfma_f32_16x16x32_bf16 v[58:61], v[158:161], v[182:185], v[58:61]
	v_mfma_f32_16x16x32_bf16 v[54:57], v[150:153], v[190:193], v[54:57]
	v_mfma_f32_16x16x32_bf16 v[46:49], v[158:161], v[190:193], v[46:49]
	v_mfma_f32_16x16x32_bf16 v[38:41], v[150:153], v[198:201], v[38:41]
	v_mfma_f32_16x16x32_bf16 v[26:29], v[158:161], v[198:201], v[26:29]
	v_mfma_f32_16x16x32_bf16 v[22:25], v[150:153], v[206:209], v[22:25]
	v_mfma_f32_16x16x32_bf16 v[14:17], v[158:161], v[206:209], v[14:17]
	v_mfma_f32_16x16x32_bf16 v[62:65], v[154:157], v[186:189], v[62:65]
	v_mfma_f32_16x16x32_bf16 v[58:61], v[162:165], v[186:189], v[58:61]
	v_mfma_f32_16x16x32_bf16 v[54:57], v[154:157], v[194:197], v[54:57]
	v_mfma_f32_16x16x32_bf16 v[46:49], v[162:165], v[194:197], v[46:49]
	v_mfma_f32_16x16x32_bf16 v[38:41], v[154:157], v[202:205], v[38:41]
	v_mfma_f32_16x16x32_bf16 v[26:29], v[162:165], v[202:205], v[26:29]
	v_mfma_f32_16x16x32_bf16 v[22:25], v[154:157], v[210:213], v[22:25]
	v_mfma_f32_16x16x32_bf16 v[14:17], v[162:165], v[210:213], v[14:17]
	s_setprio 0
	s_setprio 1
	v_mfma_f32_16x16x32_bf16 v[50:53], v[166:169], v[182:185], v[50:53]
	v_mfma_f32_16x16x32_bf16 v[42:45], v[174:177], v[182:185], v[42:45]
	v_mfma_f32_16x16x32_bf16 v[34:37], v[166:169], v[190:193], v[34:37]
	v_mfma_f32_16x16x32_bf16 v[30:33], v[174:177], v[190:193], v[30:33]
	v_mfma_f32_16x16x32_bf16 v[18:21], v[166:169], v[198:201], v[18:21]
	v_mfma_f32_16x16x32_bf16 v[10:13], v[174:177], v[198:201], v[10:13]
	v_mfma_f32_16x16x32_bf16 v[6:9], v[166:169], v[206:209], v[6:9]
	v_mfma_f32_16x16x32_bf16 v[2:5], v[174:177], v[206:209], v[2:5]
	v_mfma_f32_16x16x32_bf16 v[50:53], v[170:173], v[186:189], v[50:53]
	v_mfma_f32_16x16x32_bf16 v[42:45], v[178:181], v[186:189], v[42:45]
	v_mfma_f32_16x16x32_bf16 v[34:37], v[170:173], v[194:197], v[34:37]
	v_mfma_f32_16x16x32_bf16 v[30:33], v[178:181], v[194:197], v[30:33]
	v_mfma_f32_16x16x32_bf16 v[18:21], v[170:173], v[202:205], v[18:21]
	v_mfma_f32_16x16x32_bf16 v[10:13], v[178:181], v[202:205], v[10:13]
	v_mfma_f32_16x16x32_bf16 v[6:9], v[170:173], v[210:213], v[6:9]
	v_mfma_f32_16x16x32_bf16 v[2:5], v[178:181], v[210:213], v[2:5]
	s_add_i32 s55, s55, 2
	s_add_u32 s34, s34, 0x100
	s_addc_u32 s35, s35, 0
	s_add_u32 s53, s53, 0x100
	s_addc_u32 s54, s54, 0
	s_cmp_gt_u32 s55, 13
	s_setprio 0
	s_barrier
	s_cbranch_scc0 .LBB0_722
	v_lshl_add_u32 v198, s30, 8, v1
	v_lshl_or_b32 v142, s50, 8, v145
	s_cmpk_gt_i32 s30, 0xff
	v_ashrrev_i32_e32 v143, 31, v142
	v_or_b32_e32 v166, 16, v198
	s_cselect_b32 s35, s9, s17
	s_cselect_b32 s34, s8, s16
	v_lshlrev_b64 v[142:143], 2, v[142:143]
	v_ashrrev_i32_e32 v199, 31, v198
	v_ashrrev_i32_e32 v167, 31, v166
	v_lshl_add_u64 v[214:215], s[34:35], 0, v[142:143]
	v_lshlrev_b64 v[216:217], 12, v[198:199]
	v_lshlrev_b64 v[218:219], 12, v[166:167]
	v_lshl_add_u64 v[162:163], v[214:215], 0, v[216:217]
	v_lshl_add_u64 v[178:179], v[214:215], 0, v[218:219]
	global_load_dwordx4 v[150:153], v[162:163], off
	global_load_dwordx4 v[154:157], v[162:163], off offset:64
	global_load_dwordx4 v[158:161], v[162:163], off offset:512
	s_nop 0
	global_load_dwordx4 v[162:165], v[162:163], off offset:576
	s_nop 0
	global_load_dwordx4 v[166:169], v[178:179], off
	global_load_dwordx4 v[170:173], v[178:179], off offset:64
	global_load_dwordx4 v[174:177], v[178:179], off offset:512
	s_nop 0
	global_load_dwordx4 v[178:181], v[178:179], off offset:576
	v_or_b32_e32 v182, 32, v198
	v_or_b32_e32 v198, 48, v198
	v_ashrrev_i32_e32 v183, 31, v182
	v_ashrrev_i32_e32 v199, 31, v198
	v_lshlrev_b64 v[220:221], 12, v[182:183]
	v_lshlrev_b64 v[222:223], 12, v[198:199]
	v_lshl_add_u64 v[194:195], v[214:215], 0, v[220:221]
	v_lshl_add_u64 v[210:211], v[214:215], 0, v[222:223]
	global_load_dwordx4 v[182:185], v[194:195], off
	global_load_dwordx4 v[186:189], v[194:195], off offset:64
	global_load_dwordx4 v[190:193], v[194:195], off offset:512
	s_nop 0
	global_load_dwordx4 v[194:197], v[194:195], off offset:576
	s_nop 0
	global_load_dwordx4 v[198:201], v[210:211], off
	global_load_dwordx4 v[202:205], v[210:211], off offset:64
	global_load_dwordx4 v[206:209], v[210:211], off offset:512
	s_nop 0
	global_load_dwordx4 v[210:213], v[210:211], off offset:576
	s_waitcnt vmcnt(0)
; #define GAS __attribute__((address_space(1)))
; #define LOADX(buf, q) do { _Pragma("unroll") for (int m = 0; m < 2; ++m) _Pragma("unroll") for (int bj = 0; bj < 2; ++bj) _Pragma("unroll") for (int n = 0; n < 2; ++n) \
;             xv[buf][m][bj][n] = *(const GAS f32x4*)(xb + (size_t)(row0 + ((q) >> 1) * 128 + (2 * ((q) & 1) + m) * 16) * DM + col0 + bj * 128 + n * 16); } while (0)
;     __device__ __forceinline__ bool operator()(pg8::f32x4 (&acc)[2][2][4][2], const pg8::Unit& u, int wr, int wc, int fr, int fq) const {
;     ...
;         LOADX(0, 0); __builtin_amdgcn_sched_barrier(0);
; #pragma unroll
;         for (int q = 0; q < 4; ++q) { const int ai = q >> 1, mh = q & 1, cb_ = q & 1;
;             if (q + 1 < 4) LOADX(cb_ ^ 1, q + 1);
;             __builtin_amdgcn_sched_barrier(0);
; #pragma unroll
;             for (int m = 0; m < 2; ++m)
; #pragma unroll
;                 for (int bj = 0; bj < 2; ++bj)
; #pragma unroll
;                     for (int n = 0; n < 2; ++n) { const pg8::f32x4 a = acc[ai][bj][2 * mh + m][n]; const f32x4 x = xv[cb_][m][bj][n];
;                         *(GAS f32x4*)(out + (size_t)(row0 + ai * 128 + (2 * mh + m) * 16) * DM + col0 + bj * 128 + n * 16) = (f32x4){x.x + a.x, x.y + a.y, x.z + a.z, x.w + a.w}; }
;             __builtin_amdgcn_sched_barrier(0);
;         }
	v_pk_add_f32 v[126:127], v[126:127], v[150:151]
	v_lshl_add_u64 v[150:151], s[72:73], 0, v[216:217]
	v_lshl_add_u64 v[150:151], v[150:151], 0, v[142:143]
	v_pk_add_f32 v[116:117], v[116:117], v[160:161]
	v_pk_add_f32 v[114:115], v[114:115], v[158:159]
	global_store_dwordx4 v[150:151], v[114:117], off offset:512
	v_pk_add_f32 v[108:109], v[108:109], v[164:165]
	v_pk_add_f32 v[106:107], v[106:107], v[162:163]
	v_lshl_add_u64 v[114:115], s[72:73], 0, v[218:219]
	global_store_dwordx4 v[150:151], v[106:109], off offset:576
	v_lshl_add_u64 v[114:115], v[114:115], 0, v[142:143]
	v_pk_add_f32 v[128:129], v[128:129], v[152:153]
	v_pk_add_f32 v[108:109], v[120:121], v[168:169]
	v_pk_add_f32 v[106:107], v[118:119], v[166:167]
	v_pk_add_f32 v[124:125], v[124:125], v[156:157]
	v_pk_add_f32 v[122:123], v[122:123], v[154:155]
	global_store_dwordx4 v[114:115], v[106:109], off
	v_pk_add_f32 v[104:105], v[104:105], v[176:177]
	v_pk_add_f32 v[102:103], v[102:103], v[174:175]
	v_pk_add_f32 v[108:109], v[112:113], v[172:173]
	v_pk_add_f32 v[106:107], v[110:111], v[170:171]
	v_pk_add_f32 v[96:97], v[96:97], v[180:181]
	v_pk_add_f32 v[94:95], v[94:95], v[178:179]
	global_store_dwordx4 v[150:151], v[126:129], off
	global_store_dwordx4 v[150:151], v[122:125], off offset:64
	global_store_dwordx4 v[114:115], v[106:109], off offset:64
	global_store_dwordx4 v[114:115], v[102:105], off offset:512
	global_store_dwordx4 v[114:115], v[94:97], off offset:576
	v_lshl_add_u64 v[150:151], v[216:217], 0, s[12:13]
	v_lshl_add_u64 v[152:153], v[216:217], 0, s[14:15]
	v_lshl_add_u64 v[110:111], v[214:215], 0, v[150:151]
	v_lshl_add_u64 v[126:127], v[214:215], 0, v[152:153]
	global_load_dwordx4 v[94:97], v[110:111], off
	global_load_dwordx4 v[102:105], v[110:111], off offset:64
	global_load_dwordx4 v[106:109], v[110:111], off offset:512
	s_nop 0
	global_load_dwordx4 v[110:113], v[110:111], off offset:576
	s_nop 0
	global_load_dwordx4 v[114:117], v[126:127], off
	global_load_dwordx4 v[118:121], v[126:127], off offset:64
	global_load_dwordx4 v[122:125], v[126:127], off offset:512
	s_nop 0
	global_load_dwordx4 v[126:129], v[126:127], off offset:576
	v_lshl_add_u64 v[154:155], s[72:73], 0, v[220:221]
	v_lshl_add_u64 v[154:155], v[154:155], 0, v[142:143]
	v_pk_add_f32 v[84:85], v[84:85], v[192:193]
	v_pk_add_f32 v[82:83], v[82:83], v[190:191]
	global_store_dwordx4 v[154:155], v[82:85], off offset:512
	v_pk_add_f32 v[76:77], v[76:77], v[196:197]
	v_pk_add_f32 v[74:75], v[74:75], v[194:195]
	v_lshl_add_u64 v[82:83], s[72:73], 0, v[222:223]
	global_store_dwordx4 v[154:155], v[74:77], off offset:576
	v_lshl_add_u64 v[82:83], v[82:83], 0, v[142:143]
	v_pk_add_f32 v[100:101], v[100:101], v[184:185]
	v_pk_add_f32 v[76:77], v[88:89], v[200:201]
	v_pk_add_f32 v[74:75], v[86:87], v[198:199]
	v_pk_add_f32 v[98:99], v[98:99], v[182:183]
	v_pk_add_f32 v[92:93], v[92:93], v[188:189]
	v_pk_add_f32 v[90:91], v[90:91], v[186:187]
	global_store_dwordx4 v[82:83], v[74:77], off
	v_pk_add_f32 v[72:73], v[72:73], v[208:209]
	v_pk_add_f32 v[70:71], v[70:71], v[206:207]
	v_pk_add_f32 v[76:77], v[80:81], v[204:205]
	v_pk_add_f32 v[74:75], v[78:79], v[202:203]
	v_pk_add_f32 v[68:69], v[68:69], v[212:213]
	v_pk_add_f32 v[66:67], v[66:67], v[210:211]
	global_store_dwordx4 v[154:155], v[98:101], off
	global_store_dwordx4 v[154:155], v[90:93], off offset:64
	global_store_dwordx4 v[82:83], v[74:77], off offset:64
	global_store_dwordx4 v[82:83], v[70:73], off offset:512
	global_store_dwordx4 v[82:83], v[66:69], off offset:576
	v_lshl_add_u64 v[154:155], v[216:217], 0, s[18:19]
	v_lshl_add_u64 v[156:157], v[216:217], 0, s[20:21]
	v_lshl_add_u64 v[78:79], v[214:215], 0, v[154:155]
	v_lshl_add_u64 v[98:99], v[214:215], 0, v[156:157]
	global_load_dwordx4 v[66:69], v[78:79], off
	global_load_dwordx4 v[70:73], v[78:79], off offset:64
	global_load_dwordx4 v[74:77], v[78:79], off offset:512
	s_nop 0
	global_load_dwordx4 v[78:81], v[78:79], off offset:576
	s_nop 0
	global_load_dwordx4 v[82:85], v[98:99], off
	global_load_dwordx4 v[86:89], v[98:99], off offset:64
	global_load_dwordx4 v[90:93], v[98:99], off offset:512
	s_nop 0
	global_load_dwordx4 v[98:101], v[98:99], off offset:576
	s_waitcnt vmcnt(23)
; #define PG8_WAIT_V(n) asm volatile("s_waitcnt vmcnt(" #n ")" ::: "memory")
; #define PG8_BAR __builtin_amdgcn_s_barrier()
; #define GAS __attribute__((address_space(1)))
; #define LOADX(buf, q) do { _Pragma("unroll") for (int m = 0; m < 2; ++m) _Pragma("unroll") for (int bj = 0; bj < 2; ++bj) _Pragma("unroll") for (int n = 0; n < 2; ++n) \
;             xv[buf][m][bj][n] = *(const GAS f32x4*)(xb + (size_t)(row0 + ((q) >> 1) * 128 + (2 * ((q) & 1) + m) * 16) * DM + col0 + bj * 128 + n * 16); } while (0)
; template <class Epi, class Sched, bool ALIGN_EPI>
; __device__ __forceinline__ unsigned long long gemm_phase(PG8_LAS unsigned char* lds, const Gemm g, const Sched& S, const Epi& E, const int probe_id) {
;     ...
;         cur = nxt; cA = nA; cB = nB; ++ui;
;         if constexpr (ALIGN_EPI) { if (wr == 1) PG8_BAR; }
;     }
;     PG8_WAIT_V(0);
;     if constexpr (!ALIGN_EPI) { if (wr == 0) PG8_BAR; }
;     PG8_BAR;
;     __device__ __forceinline__ bool operator()(pg8::f32x4 (&acc)[2][2][4][2], const pg8::Unit& u, int wr, int wc, int fr, int fq) const {
;     ...
;         for (int q = 0; q < 4; ++q) { const int ai = q >> 1, mh = q & 1, cb_ = q & 1;
;             if (q + 1 < 4) LOADX(cb_ ^ 1, q + 1);
;             __builtin_amdgcn_sched_barrier(0);
; #pragma unroll
;             for (int m = 0; m < 2; ++m)
; #pragma unroll
;                 for (int bj = 0; bj < 2; ++bj)
; #pragma unroll
;                     for (int n = 0; n < 2; ++n) { const pg8::f32x4 a = acc[ai][bj][2 * mh + m][n]; const f32x4 x = xv[cb_][m][bj][n];
;                         *(GAS f32x4*)(out + (size_t)(row0 + ai * 128 + (2 * mh + m) * 16) * DM + col0 + bj * 128 + n * 16) = (f32x4){x.x + a.x, x.y + a.y, x.z + a.z, x.w + a.w}; }
;             __builtin_amdgcn_sched_barrier(0);
;         }
	v_pk_add_f32 v[62:63], v[62:63], v[94:95]
	v_lshl_add_u64 v[94:95], s[72:73], 0, v[150:151]
	v_lshl_add_u64 v[94:95], v[94:95], 0, v[142:143]
	s_waitcnt vmcnt(21)
	v_pk_add_f32 v[52:53], v[52:53], v[108:109]
	v_pk_add_f32 v[50:51], v[50:51], v[106:107]
	global_store_dwordx4 v[94:95], v[50:53], off offset:512
	s_waitcnt vmcnt(21)
	v_pk_add_f32 v[44:45], v[44:45], v[112:113]
	v_pk_add_f32 v[42:43], v[42:43], v[110:111]
	v_lshl_add_u64 v[50:51], s[72:73], 0, v[152:153]
	global_store_dwordx4 v[94:95], v[42:45], off offset:576
	v_lshl_add_u64 v[50:51], v[50:51], 0, v[142:143]
	v_pk_add_f32 v[64:65], v[64:65], v[96:97]
	s_waitcnt vmcnt(21)
	v_pk_add_f32 v[44:45], v[56:57], v[116:117]
	v_pk_add_f32 v[42:43], v[54:55], v[114:115]
	v_pk_add_f32 v[60:61], v[60:61], v[104:105]
	v_pk_add_f32 v[58:59], v[58:59], v[102:103]
	global_store_dwordx4 v[50:51], v[42:45], off
	s_waitcnt vmcnt(20)
	v_pk_add_f32 v[36:37], v[36:37], v[124:125]
	v_pk_add_f32 v[34:35], v[34:35], v[122:123]
	v_pk_add_f32 v[44:45], v[48:49], v[120:121]
	v_pk_add_f32 v[42:43], v[46:47], v[118:119]
	s_waitcnt vmcnt(19)
	v_pk_add_f32 v[32:33], v[32:33], v[128:129]
	v_pk_add_f32 v[30:31], v[30:31], v[126:127]
	global_store_dwordx4 v[94:95], v[62:65], off
	global_store_dwordx4 v[94:95], v[58:61], off offset:64
	global_store_dwordx4 v[50:51], v[42:45], off offset:64
	global_store_dwordx4 v[50:51], v[34:37], off offset:512
	global_store_dwordx4 v[50:51], v[30:33], off offset:576
	s_nop 0
	v_lshl_add_u64 v[34:35], s[72:73], 0, v[154:155]
	v_lshl_add_u64 v[34:35], v[34:35], 0, v[142:143]
	s_waitcnt vmcnt(13)
	v_pk_add_f32 v[20:21], v[20:21], v[76:77]
	v_pk_add_f32 v[18:19], v[18:19], v[74:75]
	global_store_dwordx4 v[34:35], v[18:21], off offset:512
	s_waitcnt vmcnt(13)
	v_pk_add_f32 v[12:13], v[12:13], v[80:81]
	v_pk_add_f32 v[10:11], v[10:11], v[78:79]
	v_lshl_add_u64 v[18:19], s[72:73], 0, v[156:157]
	global_store_dwordx4 v[34:35], v[10:13], off offset:576
	v_lshl_add_u64 v[18:19], v[18:19], 0, v[142:143]
	v_pk_add_f32 v[32:33], v[40:41], v[68:69]
	s_waitcnt vmcnt(13)
	v_pk_add_f32 v[12:13], v[24:25], v[84:85]
	v_pk_add_f32 v[10:11], v[22:23], v[82:83]
	v_pk_add_f32 v[30:31], v[38:39], v[66:67]
	v_pk_add_f32 v[28:29], v[28:29], v[72:73]
	v_pk_add_f32 v[26:27], v[26:27], v[70:71]
	global_store_dwordx4 v[18:19], v[10:13], off
	s_waitcnt vmcnt(12)
	v_pk_add_f32 v[8:9], v[8:9], v[92:93]
	v_pk_add_f32 v[6:7], v[6:7], v[90:91]
	v_pk_add_f32 v[12:13], v[16:17], v[88:89]
	v_pk_add_f32 v[10:11], v[14:15], v[86:87]
	s_waitcnt vmcnt(11)
	v_pk_add_f32 v[4:5], v[4:5], v[100:101]
	v_pk_add_f32 v[2:3], v[2:3], v[98:99]
	global_store_dwordx4 v[34:35], v[30:33], off
	global_store_dwordx4 v[34:35], v[26:29], off offset:64
	global_store_dwordx4 v[18:19], v[10:13], off offset:64
	global_store_dwordx4 v[18:19], v[6:9], off offset:512
	global_store_dwordx4 v[18:19], v[2:5], off offset:576
	s_and_b64 vcc, exec, s[0:1]
	s_mov_b32 s50, s22
	s_mov_b32 s30, s24
	s_mov_b64 s[36:37], s[28:29]
	s_mov_b64 s[34:35], s[26:27]
	s_cbranch_vccz .LBB0_715
	s_waitcnt vmcnt(0)
	s_cmpk_gt_u32 s2, 0xff
	s_cbranch_scc1 .LBB0_726
	s_barrier
